# NSA selected branch re-laid: S = Q K^T with queries on the score registers (only selecting queries exponentiated), P^T via quad broadcast + ds_bpermute, V^T block key order changed to match
# baseline (speedup 1.0000x reference)
.LBB0_2001:
	s_waitcnt lgkmcnt(0)
	v_cndmask_b32_e64 v202, 1.0, v218, s[12:13]
	s_add_i32 s53, s80, -4
	s_mul_hi_u32 s51, s53, 0x900000
	s_mul_i32 s53, s53, 0x900000
	s_ashr_i32 s58, s58, 6
	v_pk_mul_f32 v[146:147], v[202:203], v[146:147] op_sel_hi:[0,1]
	v_pk_mul_f32 v[144:145], v[202:203], v[144:145] op_sel_hi:[0,1]
	v_pk_mul_f32 v[148:149], v[202:203], v[154:155] op_sel_hi:[0,1]
	v_pk_mul_f32 v[150:151], v[202:203], v[152:153] op_sel_hi:[0,1]
	s_mov_b64 s[12:13], -1
	s_and_b64 vcc, exec, s[84:85]
	s_cbranch_vccz .LBB0_2013
	s_mov_b64 s[86:87], -1
	s_mov_b64 s[12:13], 0
	s_cmp_lt_i32 s80, 7
	s_mov_b64 s[82:83], 0
	s_cbranch_scc1 .LBB0_2008
	s_cmp_eq_u32 s80, 7
	s_mov_b64 s[82:83], -1
	s_cbranch_scc0 .LBB0_2005
	v_mov_b32_e32 v154, 0
	v_cvt_pk_fp8_f32 v154, v144, v145
	v_mov_b32_e32 v155, 0
	v_cvt_pk_fp8_f32 v155, v150, v151
	s_add_i32 s60, s58, s30
	v_cvt_pk_fp8_f32 v154, v146, v147 op_sel:[0,0,1]
	s_ashr_i32 s61, s60, 31
	v_cvt_pk_fp8_f32 v155, v148, v149 op_sel:[0,0,1]
	s_lshl_b64 s[60:61], s[60:61], 12
	v_lshl_add_u64 v[152:153], v[178:179], 0, s[60:61]
	v_subrev_u32_e32 v152, s38, v152
	v_lshrrev_b32_e32 v252, 2, v152
	v_and_b32_e32 v253, 0xf3, v252
	v_lshlrev_b32_e32 v252, 4, v152
	v_and_b32_e32 v252, 0x300, v252
	v_or_b32_e32 v253, v253, v252
	v_lshlrev_b32_e32 v252, 2, v152
	v_and_b32_e32 v252, 12, v252
	v_and_b32_e32 v152, 0xfffffc00, v152
	v_or3_b32 v152, v152, v253, v252
	v_add_u32_e32 v152, s38, v152
	v_lshrrev_b32_e32 v156, 8, v154
	global_store_byte v[152:153], v154, off
	global_store_byte v[152:153], v156, off offset:16
	global_store_byte_d16_hi v[152:153], v154, off offset:32
	v_lshrrev_b32_e32 v154, 24, v154
	global_store_byte v[152:153], v154, off offset:48
	global_store_byte v[152:153], v155, off offset:64
	v_lshrrev_b32_e32 v154, 8, v155
	global_store_byte v[152:153], v154, off offset:80
	global_store_byte_d16_hi v[152:153], v155, off offset:96
	v_lshrrev_b32_e32 v154, 24, v155
	global_store_byte v[152:153], v154, off offset:112
	s_mov_b64 s[82:83], 0

.LBB0_2023:
	s_waitcnt vmcnt(0)
	v_mov_b32_e32 v128, v202
	v_mov_b32_e32 v129, v202
	v_mov_b32_e32 v203, v202
	v_pk_mul_f32 v[126:127], v[128:129], v[126:127]
	v_pk_mul_f32 v[122:123], v[128:129], v[122:123]
	v_cndmask_b32_e64 v128, 0, 1, s[84:85]
	v_pk_mul_f32 v[124:125], v[202:203], v[124:125]
	v_pk_mul_f32 v[120:121], v[202:203], v[120:121]
	v_cmp_ne_u32_e64 s[12:13], 1, v128
	s_andn2_b64 vcc, exec, s[84:85]
	s_mov_b64 s[84:85], -1
	s_cbranch_vccnz .LBB0_2030
	s_mov_b64 s[88:89], -1
	s_mov_b64 s[84:85], 0
	s_cmp_lt_i32 s80, 7
	s_mov_b64 s[86:87], 0
	s_cbranch_scc1 .LBB0_2033
	s_cmp_eq_u32 s80, 7
	s_mov_b64 s[86:87], -1
	s_cbranch_scc0 .LBB0_2027
	v_mov_b32_e32 v130, v171
	v_cvt_pk_fp8_f32 v130, v124, v125
	v_mov_b32_e32 v131, v171
	v_cvt_pk_fp8_f32 v131, v120, v121
	s_add_i32 s60, s58, s33
	v_cvt_pk_fp8_f32 v130, v126, v127 op_sel:[0,0,1]
	s_ashr_i32 s61, s60, 31
	v_cvt_pk_fp8_f32 v131, v122, v123 op_sel:[0,0,1]
	s_lshl_b64 s[60:61], s[60:61], 12
	v_lshl_add_u64 v[128:129], v[182:183], 0, s[60:61]
	v_subrev_u32_e32 v128, s38, v128
	v_lshrrev_b32_e32 v252, 2, v128
	v_and_b32_e32 v253, 0xf3, v252
	v_lshlrev_b32_e32 v252, 4, v128
	v_and_b32_e32 v252, 0x300, v252
	v_or_b32_e32 v253, v253, v252
	v_lshlrev_b32_e32 v252, 2, v128
	v_and_b32_e32 v252, 12, v252
	v_and_b32_e32 v128, 0xfffffc00, v128
	v_or3_b32 v128, v128, v253, v252
	v_add_u32_e32 v128, s38, v128
	v_lshrrev_b32_e32 v132, 8, v130
	global_store_byte v[128:129], v130, off
	global_store_byte v[128:129], v132, off offset:16
	global_store_byte_d16_hi v[128:129], v130, off offset:32
	v_lshrrev_b32_e32 v130, 24, v130
	global_store_byte v[128:129], v130, off offset:48
	global_store_byte v[128:129], v131, off offset:64
	v_lshrrev_b32_e32 v130, 8, v131
	global_store_byte v[128:129], v130, off offset:80
	global_store_byte_d16_hi v[128:129], v131, off offset:96
	v_lshrrev_b32_e32 v130, 24, v131
	global_store_byte v[128:129], v130, off offset:112
	s_mov_b64 s[86:87], 0

.LBB0_2048:
	s_waitcnt lgkmcnt(6)
	v_mov_b32_e32 v140, v202
	s_waitcnt lgkmcnt(4)
	v_mov_b32_e32 v141, v202
	v_pk_mul_f32 v[138:139], v[140:141], v[138:139]
	v_pk_mul_f32 v[136:137], v[202:203], v[136:137]
	v_pk_mul_f32 v[140:141], v[140:141], v[146:147]
	v_pk_mul_f32 v[142:143], v[202:203], v[144:145]
	s_and_b64 vcc, exec, s[12:13]
	s_mov_b64 s[84:85], -1
	s_cbranch_vccnz .LBB0_2060
	s_mov_b64 s[88:89], -1
	s_mov_b64 s[84:85], 0
	s_cmp_lt_i32 s80, 7
	s_mov_b64 s[86:87], 0
	s_cbranch_scc1 .LBB0_2055
	s_cmp_eq_u32 s80, 7
	s_mov_b64 s[86:87], -1
	s_cbranch_scc0 .LBB0_2052
	v_mov_b32_e32 v146, v171
	v_cvt_pk_fp8_f32 v146, v136, v137
	v_mov_b32_e32 v147, v171
	v_cvt_pk_fp8_f32 v147, v142, v143
	s_add_i32 s60, s58, s30
	v_cvt_pk_fp8_f32 v146, v138, v139 op_sel:[0,0,1]
	s_ashr_i32 s61, s60, 31
	v_cvt_pk_fp8_f32 v147, v140, v141 op_sel:[0,0,1]
	s_lshl_b64 s[60:61], s[60:61], 12
	v_lshl_add_u64 v[144:145], v[178:179], 0, s[60:61]
	v_subrev_u32_e32 v144, s38, v144
	v_lshrrev_b32_e32 v252, 2, v144
	v_and_b32_e32 v253, 0xf3, v252
	v_lshlrev_b32_e32 v252, 4, v144
	v_and_b32_e32 v252, 0x300, v252
	v_or_b32_e32 v253, v253, v252
	v_lshlrev_b32_e32 v252, 2, v144
	v_and_b32_e32 v252, 12, v252
	v_and_b32_e32 v144, 0xfffffc00, v144
	v_or3_b32 v144, v144, v253, v252
	v_add_u32_e32 v144, s38, v144
	v_lshrrev_b32_e32 v148, 8, v146
	global_store_byte v[144:145], v146, off offset:1
	global_store_byte v[144:145], v148, off offset:17
	global_store_byte_d16_hi v[144:145], v146, off offset:33
	v_lshrrev_b32_e32 v146, 24, v146
	global_store_byte v[144:145], v146, off offset:49
	global_store_byte v[144:145], v147, off offset:65
	v_lshrrev_b32_e32 v146, 8, v147
	global_store_byte v[144:145], v146, off offset:81
	global_store_byte_d16_hi v[144:145], v147, off offset:97
	v_lshrrev_b32_e32 v146, 24, v147
	global_store_byte v[144:145], v146, off offset:113
	s_mov_b64 s[86:87], 0

.LBB0_2070:
	s_waitcnt vmcnt(3)
	v_mov_b32_e32 v120, v202
	v_mov_b32_e32 v121, v202
	v_pk_mul_f32 v[118:119], v[120:121], v[118:119]
	v_pk_mul_f32 v[116:117], v[202:203], v[116:117]
	v_pk_mul_f32 v[114:115], v[120:121], v[114:115]
	v_pk_mul_f32 v[112:113], v[202:203], v[112:113]
	s_and_b64 vcc, exec, s[12:13]
	s_mov_b64 s[84:85], -1
	s_cbranch_vccnz .LBB0_2077
	s_mov_b64 s[88:89], -1
	s_mov_b64 s[84:85], 0
	s_cmp_lt_i32 s80, 7
	s_mov_b64 s[86:87], 0
	s_cbranch_scc1 .LBB0_2080
	s_cmp_eq_u32 s80, 7
	s_mov_b64 s[86:87], -1
	s_cbranch_scc0 .LBB0_2074
	v_mov_b32_e32 v122, v171
	v_cvt_pk_fp8_f32 v122, v116, v117
	v_mov_b32_e32 v123, v171
	v_cvt_pk_fp8_f32 v123, v112, v113
	s_add_i32 s60, s58, s33
	v_cvt_pk_fp8_f32 v122, v118, v119 op_sel:[0,0,1]
	s_ashr_i32 s61, s60, 31
	v_cvt_pk_fp8_f32 v123, v114, v115 op_sel:[0,0,1]
	s_lshl_b64 s[60:61], s[60:61], 12
	v_lshl_add_u64 v[120:121], v[182:183], 0, s[60:61]
	v_subrev_u32_e32 v120, s38, v120
	v_lshrrev_b32_e32 v252, 2, v120
	v_and_b32_e32 v253, 0xf3, v252
	v_lshlrev_b32_e32 v252, 4, v120
	v_and_b32_e32 v252, 0x300, v252
	v_or_b32_e32 v253, v253, v252
	v_lshlrev_b32_e32 v252, 2, v120
	v_and_b32_e32 v252, 12, v252
	v_and_b32_e32 v120, 0xfffffc00, v120
	v_or3_b32 v120, v120, v253, v252
	v_add_u32_e32 v120, s38, v120
	s_waitcnt vmcnt(1)
	v_lshrrev_b32_e32 v124, 8, v122
	global_store_byte v[120:121], v122, off offset:1
	global_store_byte v[120:121], v124, off offset:17
	global_store_byte_d16_hi v[120:121], v122, off offset:33
	v_lshrrev_b32_e32 v122, 24, v122
	global_store_byte v[120:121], v122, off offset:49
	global_store_byte v[120:121], v123, off offset:65
	v_lshrrev_b32_e32 v122, 8, v123
	global_store_byte v[120:121], v122, off offset:81
	global_store_byte_d16_hi v[120:121], v123, off offset:97
	v_lshrrev_b32_e32 v122, 24, v123
	global_store_byte v[120:121], v122, off offset:113
	s_mov_b64 s[86:87], 0

.LBB0_2095:
	s_waitcnt vmcnt(0) lgkmcnt(6)
	v_mov_b32_e32 v132, v202
	s_waitcnt lgkmcnt(4)
	v_mov_b32_e32 v133, v202
	v_pk_mul_f32 v[130:131], v[132:133], v[130:131]
	v_pk_mul_f32 v[128:129], v[202:203], v[128:129]
	v_pk_mul_f32 v[132:133], v[132:133], v[138:139]
	v_pk_mul_f32 v[134:135], v[202:203], v[136:137]
	s_and_b64 vcc, exec, s[12:13]
	s_mov_b64 s[84:85], -1
	s_cbranch_vccnz .LBB0_2107
	s_mov_b64 s[88:89], -1
	s_mov_b64 s[84:85], 0
	s_cmp_lt_i32 s80, 7
	s_mov_b64 s[86:87], 0
	s_cbranch_scc1 .LBB0_2102
	s_cmp_eq_u32 s80, 7
	s_mov_b64 s[86:87], -1
	s_cbranch_scc0 .LBB0_2099
	v_mov_b32_e32 v138, v171
	v_cvt_pk_fp8_f32 v138, v128, v129
	v_mov_b32_e32 v139, v171
	v_cvt_pk_fp8_f32 v139, v134, v135
	s_add_i32 s60, s58, s30
	v_cvt_pk_fp8_f32 v138, v130, v131 op_sel:[0,0,1]
	s_ashr_i32 s61, s60, 31
	v_cvt_pk_fp8_f32 v139, v132, v133 op_sel:[0,0,1]
	s_lshl_b64 s[60:61], s[60:61], 12
	v_lshl_add_u64 v[136:137], v[178:179], 0, s[60:61]
	v_subrev_u32_e32 v136, s38, v136
	v_lshrrev_b32_e32 v252, 2, v136
	v_and_b32_e32 v253, 0xf3, v252
	v_lshlrev_b32_e32 v252, 4, v136
	v_and_b32_e32 v252, 0x300, v252
	v_or_b32_e32 v253, v253, v252
	v_lshlrev_b32_e32 v252, 2, v136
	v_and_b32_e32 v252, 12, v252
	v_and_b32_e32 v136, 0xfffffc00, v136
	v_or3_b32 v136, v136, v253, v252
	v_add_u32_e32 v136, s38, v136
	v_lshrrev_b32_e32 v140, 8, v138
	global_store_byte v[136:137], v138, off offset:2
	global_store_byte v[136:137], v140, off offset:18
	global_store_byte_d16_hi v[136:137], v138, off offset:34
	v_lshrrev_b32_e32 v138, 24, v138
	global_store_byte v[136:137], v138, off offset:50
	global_store_byte v[136:137], v139, off offset:66
	v_lshrrev_b32_e32 v138, 8, v139
	global_store_byte v[136:137], v138, off offset:82
	global_store_byte_d16_hi v[136:137], v139, off offset:98
	v_lshrrev_b32_e32 v138, 24, v139
	global_store_byte v[136:137], v138, off offset:114
	s_mov_b64 s[86:87], 0

.LBB0_2117:
	v_mov_b32_e32 v112, v202
	v_mov_b32_e32 v113, v202
	v_pk_mul_f32 v[110:111], v[112:113], v[110:111]
	v_pk_mul_f32 v[108:109], v[202:203], v[108:109]
	v_pk_mul_f32 v[106:107], v[112:113], v[106:107]
	v_pk_mul_f32 v[104:105], v[202:203], v[104:105]
	s_and_b64 vcc, exec, s[12:13]
	s_mov_b64 s[84:85], -1
	s_cbranch_vccnz .LBB0_2124
	s_mov_b64 s[88:89], -1
	s_mov_b64 s[84:85], 0
	s_cmp_lt_i32 s80, 7
	s_mov_b64 s[86:87], 0
	s_cbranch_scc1 .LBB0_2127
	s_cmp_eq_u32 s80, 7
	s_mov_b64 s[86:87], -1
	s_cbranch_scc0 .LBB0_2121
	v_mov_b32_e32 v114, v171
	v_cvt_pk_fp8_f32 v114, v108, v109
	v_mov_b32_e32 v115, v171
	v_cvt_pk_fp8_f32 v115, v104, v105
	s_add_i32 s60, s58, s33
	v_cvt_pk_fp8_f32 v114, v110, v111 op_sel:[0,0,1]
	s_ashr_i32 s61, s60, 31
	v_cvt_pk_fp8_f32 v115, v106, v107 op_sel:[0,0,1]
	s_lshl_b64 s[60:61], s[60:61], 12
	v_lshl_add_u64 v[112:113], v[182:183], 0, s[60:61]
	v_subrev_u32_e32 v112, s38, v112
	v_lshrrev_b32_e32 v252, 2, v112
	v_and_b32_e32 v253, 0xf3, v252
	v_lshlrev_b32_e32 v252, 4, v112
	v_and_b32_e32 v252, 0x300, v252
	v_or_b32_e32 v253, v253, v252
	v_lshlrev_b32_e32 v252, 2, v112
	v_and_b32_e32 v252, 12, v252
	v_and_b32_e32 v112, 0xfffffc00, v112
	v_or3_b32 v112, v112, v253, v252
	v_add_u32_e32 v112, s38, v112
	v_lshrrev_b32_e32 v116, 8, v114
	global_store_byte v[112:113], v114, off offset:2
	global_store_byte v[112:113], v116, off offset:18
	global_store_byte_d16_hi v[112:113], v114, off offset:34
	v_lshrrev_b32_e32 v114, 24, v114
	global_store_byte v[112:113], v114, off offset:50
	global_store_byte v[112:113], v115, off offset:66
	v_lshrrev_b32_e32 v114, 8, v115
	global_store_byte v[112:113], v114, off offset:82
	global_store_byte_d16_hi v[112:113], v115, off offset:98
	v_lshrrev_b32_e32 v114, 24, v115
	global_store_byte v[112:113], v114, off offset:114
	s_mov_b64 s[86:87], 0

.LBB0_2142:
	s_waitcnt lgkmcnt(6)
	v_mov_b32_e32 v124, v202
	s_waitcnt lgkmcnt(4)
	v_mov_b32_e32 v125, v202
	v_pk_mul_f32 v[122:123], v[124:125], v[122:123]
	v_pk_mul_f32 v[120:121], v[202:203], v[120:121]
	v_pk_mul_f32 v[124:125], v[124:125], v[130:131]
	v_pk_mul_f32 v[126:127], v[202:203], v[128:129]
	s_and_b64 vcc, exec, s[12:13]
	s_mov_b64 s[84:85], -1
	s_cbranch_vccnz .LBB0_2154
	s_mov_b64 s[88:89], -1
	s_mov_b64 s[84:85], 0
	s_cmp_lt_i32 s80, 7
	s_mov_b64 s[86:87], 0
	s_cbranch_scc1 .LBB0_2149
	s_cmp_eq_u32 s80, 7
	s_mov_b64 s[86:87], -1
	s_cbranch_scc0 .LBB0_2146
	v_mov_b32_e32 v130, v171
	v_cvt_pk_fp8_f32 v130, v120, v121
	v_mov_b32_e32 v131, v171
	v_cvt_pk_fp8_f32 v131, v126, v127
	s_add_i32 s60, s58, s30
	v_cvt_pk_fp8_f32 v130, v122, v123 op_sel:[0,0,1]
	s_ashr_i32 s61, s60, 31
	v_cvt_pk_fp8_f32 v131, v124, v125 op_sel:[0,0,1]
	s_lshl_b64 s[60:61], s[60:61], 12
	v_lshl_add_u64 v[128:129], v[186:187], 0, s[60:61]
	v_subrev_u32_e32 v128, s38, v128
	v_lshrrev_b32_e32 v252, 2, v128
	v_and_b32_e32 v253, 0xf3, v252
	v_lshlrev_b32_e32 v252, 4, v128
	v_and_b32_e32 v252, 0x300, v252
	v_or_b32_e32 v253, v253, v252
	v_lshlrev_b32_e32 v252, 2, v128
	v_and_b32_e32 v252, 12, v252
	v_and_b32_e32 v128, 0xfffffc00, v128
	v_or3_b32 v128, v128, v253, v252
	v_add_u32_e32 v128, s38, v128
	v_lshrrev_b32_e32 v132, 8, v130
	global_store_byte v[128:129], v130, off
	global_store_byte v[128:129], v132, off offset:16
	global_store_byte_d16_hi v[128:129], v130, off offset:32
	v_lshrrev_b32_e32 v130, 24, v130
	global_store_byte v[128:129], v130, off offset:48
	global_store_byte v[128:129], v131, off offset:64
	v_lshrrev_b32_e32 v130, 8, v131
	global_store_byte v[128:129], v130, off offset:80
	global_store_byte_d16_hi v[128:129], v131, off offset:96
	v_lshrrev_b32_e32 v130, 24, v131
	global_store_byte v[128:129], v130, off offset:112
	s_mov_b64 s[86:87], 0

.LBB0_2164:
	s_waitcnt vmcnt(3)
	v_mov_b32_e32 v104, v202
	v_mov_b32_e32 v105, v202
	v_pk_mul_f32 v[102:103], v[104:105], v[102:103]
	v_pk_mul_f32 v[100:101], v[202:203], v[100:101]
	v_pk_mul_f32 v[98:99], v[104:105], v[98:99]
	v_pk_mul_f32 v[96:97], v[202:203], v[96:97]
	s_and_b64 vcc, exec, s[12:13]
	s_mov_b64 s[84:85], -1
	s_cbranch_vccnz .LBB0_2171
	s_mov_b64 s[88:89], -1
	s_mov_b64 s[84:85], 0
	s_cmp_lt_i32 s80, 7
	s_mov_b64 s[86:87], 0
	s_cbranch_scc1 .LBB0_2174
	s_cmp_eq_u32 s80, 7
	s_mov_b64 s[86:87], -1
	s_cbranch_scc0 .LBB0_2168
	v_mov_b32_e32 v106, v171
	v_cvt_pk_fp8_f32 v106, v100, v101
	v_mov_b32_e32 v107, v171
	v_cvt_pk_fp8_f32 v107, v96, v97
	s_add_i32 s58, s58, s33
	v_cvt_pk_fp8_f32 v106, v102, v103 op_sel:[0,0,1]
	s_ashr_i32 s59, s58, 31
	v_cvt_pk_fp8_f32 v107, v98, v99 op_sel:[0,0,1]
	s_lshl_b64 s[58:59], s[58:59], 12
	v_lshl_add_u64 v[104:105], v[188:189], 0, s[58:59]
	v_subrev_u32_e32 v104, s38, v104
	v_lshrrev_b32_e32 v252, 2, v104
	v_and_b32_e32 v253, 0xf3, v252
	v_lshlrev_b32_e32 v252, 4, v104
	v_and_b32_e32 v252, 0x300, v252
	v_or_b32_e32 v253, v253, v252
	v_lshlrev_b32_e32 v252, 2, v104
	v_and_b32_e32 v252, 12, v252
	v_and_b32_e32 v104, 0xfffffc00, v104
	v_or3_b32 v104, v104, v253, v252
	v_add_u32_e32 v104, s38, v104
	s_waitcnt vmcnt(1)
	v_lshrrev_b32_e32 v108, 8, v106
	global_store_byte v[104:105], v106, off
	global_store_byte v[104:105], v108, off offset:16
	global_store_byte_d16_hi v[104:105], v106, off offset:32
	v_lshrrev_b32_e32 v106, 24, v106
	global_store_byte v[104:105], v106, off offset:48
	global_store_byte v[104:105], v107, off offset:64
	v_lshrrev_b32_e32 v106, 8, v107
	global_store_byte v[104:105], v106, off offset:80
	global_store_byte_d16_hi v[104:105], v107, off offset:96
	v_lshrrev_b32_e32 v106, 24, v107
	global_store_byte v[104:105], v106, off offset:112
	s_mov_b64 s[86:87], 0

.LBB0_2189:
	s_waitcnt vmcnt(0) lgkmcnt(6)
	v_mov_b32_e32 v116, v202
	s_waitcnt lgkmcnt(4)
	v_mov_b32_e32 v117, v202
	v_ashrrev_i32_e32 v136, 6, v128
	v_pk_mul_f32 v[114:115], v[116:117], v[114:115]
	v_pk_mul_f32 v[112:113], v[202:203], v[112:113]
	v_pk_mul_f32 v[116:117], v[116:117], v[122:123]
	v_pk_mul_f32 v[118:119], v[202:203], v[120:121]
	s_and_b64 vcc, exec, s[12:13]
	s_mov_b64 s[84:85], -1
	s_cbranch_vccnz .LBB0_2201
	s_mov_b64 s[88:89], -1
	s_mov_b64 s[84:85], 0
	s_cmp_lt_i32 s80, 7
	s_mov_b64 s[86:87], 0
	s_cbranch_scc1 .LBB0_2196
	s_cmp_eq_u32 s80, 7
	s_mov_b64 s[86:87], -1
	s_cbranch_scc0 .LBB0_2193
	v_mov_b32_e32 v122, v171
	v_cvt_pk_fp8_f32 v122, v112, v113
	v_mov_b32_e32 v123, v171
	v_cvt_pk_fp8_f32 v123, v118, v119
	v_add_u32_e32 v120, s30, v136
	v_cvt_pk_fp8_f32 v122, v114, v115 op_sel:[0,0,1]
	v_ashrrev_i32_e32 v121, 31, v120
	v_cvt_pk_fp8_f32 v123, v116, v117 op_sel:[0,0,1]
	v_lshlrev_b64 v[120:121], 12, v[120:121]
	v_lshl_add_u64 v[120:121], v[178:179], 0, v[120:121]
	v_subrev_u32_e32 v120, s38, v120
	v_lshrrev_b32_e32 v252, 2, v120
	v_and_b32_e32 v253, 0xf3, v252
	v_lshlrev_b32_e32 v252, 4, v120
	v_and_b32_e32 v252, 0x300, v252
	v_or_b32_e32 v253, v253, v252
	v_lshlrev_b32_e32 v252, 2, v120
	v_and_b32_e32 v252, 12, v252
	v_and_b32_e32 v120, 0xfffffc00, v120
	v_or3_b32 v120, v120, v253, v252
	v_add_u32_e32 v120, s38, v120
	v_lshrrev_b32_e32 v124, 8, v122
	global_store_byte v[120:121], v122, off
	global_store_byte v[120:121], v124, off offset:16
	global_store_byte_d16_hi v[120:121], v122, off offset:32
	v_lshrrev_b32_e32 v122, 24, v122
	global_store_byte v[120:121], v122, off offset:48
	global_store_byte v[120:121], v123, off offset:64
	v_lshrrev_b32_e32 v122, 8, v123
	global_store_byte v[120:121], v122, off offset:80
	global_store_byte_d16_hi v[120:121], v123, off offset:96
	v_lshrrev_b32_e32 v122, 24, v123
	global_store_byte v[120:121], v122, off offset:112
	s_mov_b64 s[86:87], 0

.LBB0_2211:
	v_mov_b32_e32 v96, v202
	v_mov_b32_e32 v97, v202
	v_pk_mul_f32 v[94:95], v[96:97], v[94:95]
	v_pk_mul_f32 v[92:93], v[202:203], v[92:93]
	v_pk_mul_f32 v[90:91], v[96:97], v[90:91]
	v_pk_mul_f32 v[88:89], v[202:203], v[88:89]
	s_and_b64 vcc, exec, s[12:13]
	s_mov_b64 s[84:85], -1
	s_cbranch_vccnz .LBB0_2218
	s_mov_b64 s[88:89], -1
	s_mov_b64 s[84:85], 0
	s_cmp_lt_i32 s80, 7
	s_mov_b64 s[86:87], 0
	s_cbranch_scc1 .LBB0_2221
	s_cmp_eq_u32 s80, 7
	s_mov_b64 s[86:87], -1
	s_cbranch_scc0 .LBB0_2215
	v_mov_b32_e32 v98, v171
	v_cvt_pk_fp8_f32 v98, v92, v93
	v_mov_b32_e32 v99, v171
	v_cvt_pk_fp8_f32 v99, v88, v89
	v_add_u32_e32 v96, s33, v136
	v_cvt_pk_fp8_f32 v98, v94, v95 op_sel:[0,0,1]
	v_ashrrev_i32_e32 v97, 31, v96
	v_cvt_pk_fp8_f32 v99, v90, v91 op_sel:[0,0,1]
	v_lshlrev_b64 v[96:97], 12, v[96:97]
	v_lshl_add_u64 v[96:97], v[182:183], 0, v[96:97]
	v_subrev_u32_e32 v96, s38, v96
	v_lshrrev_b32_e32 v252, 2, v96
	v_and_b32_e32 v253, 0xf3, v252
	v_lshlrev_b32_e32 v252, 4, v96
	v_and_b32_e32 v252, 0x300, v252
	v_or_b32_e32 v253, v253, v252
	v_lshlrev_b32_e32 v252, 2, v96
	v_and_b32_e32 v252, 12, v252
	v_and_b32_e32 v96, 0xfffffc00, v96
	v_or3_b32 v96, v96, v253, v252
	v_add_u32_e32 v96, s38, v96
	v_lshrrev_b32_e32 v100, 8, v98
	global_store_byte v[96:97], v98, off
	global_store_byte v[96:97], v100, off offset:16
	global_store_byte_d16_hi v[96:97], v98, off offset:32
	v_lshrrev_b32_e32 v98, 24, v98
	global_store_byte v[96:97], v98, off offset:48
	global_store_byte v[96:97], v99, off offset:64
	v_lshrrev_b32_e32 v98, 8, v99
	global_store_byte v[96:97], v98, off offset:80
	global_store_byte_d16_hi v[96:97], v99, off offset:96
	v_lshrrev_b32_e32 v98, 24, v99
	global_store_byte v[96:97], v98, off offset:112
	s_mov_b64 s[86:87], 0

.LBB0_2236:
	s_waitcnt lgkmcnt(6)
	v_mov_b32_e32 v108, v202
	s_waitcnt lgkmcnt(4)
	v_mov_b32_e32 v109, v202
	v_pk_mul_f32 v[106:107], v[108:109], v[106:107]
	v_pk_mul_f32 v[104:105], v[202:203], v[104:105]
	v_pk_mul_f32 v[108:109], v[108:109], v[114:115]
	v_pk_mul_f32 v[110:111], v[202:203], v[112:113]
	s_and_b64 vcc, exec, s[12:13]
	s_mov_b64 s[84:85], -1
	s_cbranch_vccnz .LBB0_2248
	s_mov_b64 s[88:89], -1
	s_mov_b64 s[84:85], 0
	s_cmp_lt_i32 s80, 7
	s_mov_b64 s[86:87], 0
	s_cbranch_scc1 .LBB0_2243
	s_cmp_eq_u32 s80, 7
	s_mov_b64 s[86:87], -1
	s_cbranch_scc0 .LBB0_2240
	v_mov_b32_e32 v114, v171
	v_cvt_pk_fp8_f32 v114, v104, v105
	v_mov_b32_e32 v115, v171
	v_cvt_pk_fp8_f32 v115, v110, v111
	v_add_u32_e32 v112, s30, v136
	v_cvt_pk_fp8_f32 v114, v106, v107 op_sel:[0,0,1]
	v_ashrrev_i32_e32 v113, 31, v112
	v_cvt_pk_fp8_f32 v115, v108, v109 op_sel:[0,0,1]
	v_lshlrev_b64 v[112:113], 12, v[112:113]
	v_lshl_add_u64 v[112:113], v[178:179], 0, v[112:113]
	v_subrev_u32_e32 v112, s38, v112
	v_lshrrev_b32_e32 v252, 2, v112
	v_and_b32_e32 v253, 0xf3, v252
	v_lshlrev_b32_e32 v252, 4, v112
	v_and_b32_e32 v252, 0x300, v252
	v_or_b32_e32 v253, v253, v252
	v_lshlrev_b32_e32 v252, 2, v112
	v_and_b32_e32 v252, 12, v252
	v_and_b32_e32 v112, 0xfffffc00, v112
	v_or3_b32 v112, v112, v253, v252
	v_add_u32_e32 v112, s38, v112
	v_lshrrev_b32_e32 v116, 8, v114
	global_store_byte v[112:113], v114, off offset:1
	global_store_byte v[112:113], v116, off offset:17
	global_store_byte_d16_hi v[112:113], v114, off offset:33
	v_lshrrev_b32_e32 v114, 24, v114
	global_store_byte v[112:113], v114, off offset:49
	global_store_byte v[112:113], v115, off offset:65
	v_lshrrev_b32_e32 v114, 8, v115
	global_store_byte v[112:113], v114, off offset:81
	global_store_byte_d16_hi v[112:113], v115, off offset:97
	v_lshrrev_b32_e32 v114, 24, v115
	global_store_byte v[112:113], v114, off offset:113
	s_mov_b64 s[86:87], 0

.LBB0_2258:
	s_waitcnt vmcnt(3)
	v_mov_b32_e32 v88, v202
	v_mov_b32_e32 v89, v202
	v_pk_mul_f32 v[86:87], v[88:89], v[86:87]
	v_pk_mul_f32 v[84:85], v[202:203], v[84:85]
	v_pk_mul_f32 v[82:83], v[88:89], v[82:83]
	v_pk_mul_f32 v[80:81], v[202:203], v[80:81]
	s_and_b64 vcc, exec, s[12:13]
	s_mov_b64 s[84:85], -1
	s_cbranch_vccnz .LBB0_2265
	s_mov_b64 s[88:89], -1
	s_mov_b64 s[84:85], 0
	s_cmp_lt_i32 s80, 7
	s_mov_b64 s[86:87], 0
	s_cbranch_scc1 .LBB0_2268
	s_cmp_eq_u32 s80, 7
	s_mov_b64 s[86:87], -1
	s_cbranch_scc0 .LBB0_2262
	v_mov_b32_e32 v90, v171
	v_cvt_pk_fp8_f32 v90, v84, v85
	v_mov_b32_e32 v91, v171
	v_cvt_pk_fp8_f32 v91, v80, v81
	v_add_u32_e32 v88, s33, v136
	v_cvt_pk_fp8_f32 v90, v86, v87 op_sel:[0,0,1]
	v_ashrrev_i32_e32 v89, 31, v88
	v_cvt_pk_fp8_f32 v91, v82, v83 op_sel:[0,0,1]
	v_lshlrev_b64 v[88:89], 12, v[88:89]
	v_lshl_add_u64 v[88:89], v[182:183], 0, v[88:89]
	v_subrev_u32_e32 v88, s38, v88
	v_lshrrev_b32_e32 v252, 2, v88
	v_and_b32_e32 v253, 0xf3, v252
	v_lshlrev_b32_e32 v252, 4, v88
	v_and_b32_e32 v252, 0x300, v252
	v_or_b32_e32 v253, v253, v252
	v_lshlrev_b32_e32 v252, 2, v88
	v_and_b32_e32 v252, 12, v252
	v_and_b32_e32 v88, 0xfffffc00, v88
	v_or3_b32 v88, v88, v253, v252
	v_add_u32_e32 v88, s38, v88
	s_waitcnt vmcnt(1)
	v_lshrrev_b32_e32 v92, 8, v90
	global_store_byte v[88:89], v90, off offset:1
	global_store_byte v[88:89], v92, off offset:17
	global_store_byte_d16_hi v[88:89], v90, off offset:33
	v_lshrrev_b32_e32 v90, 24, v90
	global_store_byte v[88:89], v90, off offset:49
	global_store_byte v[88:89], v91, off offset:65
	v_lshrrev_b32_e32 v90, 8, v91
	global_store_byte v[88:89], v90, off offset:81
	global_store_byte_d16_hi v[88:89], v91, off offset:97
	v_lshrrev_b32_e32 v90, 24, v91
	global_store_byte v[88:89], v90, off offset:113
	s_mov_b64 s[86:87], 0

.LBB0_2283:
	s_waitcnt vmcnt(0) lgkmcnt(6)
	v_mov_b32_e32 v100, v202
	s_waitcnt lgkmcnt(4)
	v_mov_b32_e32 v101, v202
	v_pk_mul_f32 v[98:99], v[100:101], v[98:99]
	v_pk_mul_f32 v[96:97], v[202:203], v[96:97]
	v_pk_mul_f32 v[100:101], v[100:101], v[106:107]
	v_pk_mul_f32 v[102:103], v[202:203], v[104:105]
	s_and_b64 vcc, exec, s[12:13]
	s_mov_b64 s[84:85], -1
	s_cbranch_vccnz .LBB0_2295
	s_mov_b64 s[88:89], -1
	s_mov_b64 s[84:85], 0
	s_cmp_lt_i32 s80, 7
	s_mov_b64 s[86:87], 0
	s_cbranch_scc1 .LBB0_2290
	s_cmp_eq_u32 s80, 7
	s_mov_b64 s[86:87], -1
	s_cbranch_scc0 .LBB0_2287
	v_mov_b32_e32 v106, v171
	v_cvt_pk_fp8_f32 v106, v96, v97
	v_mov_b32_e32 v107, v171
	v_cvt_pk_fp8_f32 v107, v102, v103
	v_add_u32_e32 v104, s30, v136
	v_cvt_pk_fp8_f32 v106, v98, v99 op_sel:[0,0,1]
	v_ashrrev_i32_e32 v105, 31, v104
	v_cvt_pk_fp8_f32 v107, v100, v101 op_sel:[0,0,1]
	v_lshlrev_b64 v[104:105], 12, v[104:105]
	v_lshl_add_u64 v[104:105], v[178:179], 0, v[104:105]
	v_subrev_u32_e32 v104, s38, v104
	v_lshrrev_b32_e32 v252, 2, v104
	v_and_b32_e32 v253, 0xf3, v252
	v_lshlrev_b32_e32 v252, 4, v104
	v_and_b32_e32 v252, 0x300, v252
	v_or_b32_e32 v253, v253, v252
	v_lshlrev_b32_e32 v252, 2, v104
	v_and_b32_e32 v252, 12, v252
	v_and_b32_e32 v104, 0xfffffc00, v104
	v_or3_b32 v104, v104, v253, v252
	v_add_u32_e32 v104, s38, v104
	v_lshrrev_b32_e32 v108, 8, v106
	global_store_byte v[104:105], v106, off offset:2
	global_store_byte v[104:105], v108, off offset:18
	global_store_byte_d16_hi v[104:105], v106, off offset:34
	v_lshrrev_b32_e32 v106, 24, v106
	global_store_byte v[104:105], v106, off offset:50
	global_store_byte v[104:105], v107, off offset:66
	v_lshrrev_b32_e32 v106, 8, v107
	global_store_byte v[104:105], v106, off offset:82
	global_store_byte_d16_hi v[104:105], v107, off offset:98
	v_lshrrev_b32_e32 v106, 24, v107
	global_store_byte v[104:105], v106, off offset:114
	s_mov_b64 s[86:87], 0

.LBB0_2305:
	v_mov_b32_e32 v80, v202
	v_mov_b32_e32 v81, v202
	v_pk_mul_f32 v[78:79], v[80:81], v[78:79]
	v_pk_mul_f32 v[76:77], v[202:203], v[76:77]
	v_pk_mul_f32 v[74:75], v[80:81], v[74:75]
	v_pk_mul_f32 v[72:73], v[202:203], v[72:73]
	s_and_b64 vcc, exec, s[12:13]
	s_mov_b64 s[84:85], -1
	s_cbranch_vccnz .LBB0_2312
	s_mov_b64 s[88:89], -1
	s_mov_b64 s[84:85], 0
	s_cmp_lt_i32 s80, 7
	s_mov_b64 s[86:87], 0
	s_cbranch_scc1 .LBB0_2315
	s_cmp_eq_u32 s80, 7
	s_mov_b64 s[86:87], -1
	s_cbranch_scc0 .LBB0_2309
	v_mov_b32_e32 v82, v171
	v_cvt_pk_fp8_f32 v82, v76, v77
	v_mov_b32_e32 v83, v171
	v_cvt_pk_fp8_f32 v83, v72, v73
	v_add_u32_e32 v80, s33, v136
	v_cvt_pk_fp8_f32 v82, v78, v79 op_sel:[0,0,1]
	v_ashrrev_i32_e32 v81, 31, v80
	v_cvt_pk_fp8_f32 v83, v74, v75 op_sel:[0,0,1]
	v_lshlrev_b64 v[80:81], 12, v[80:81]
	v_lshl_add_u64 v[80:81], v[182:183], 0, v[80:81]
	v_subrev_u32_e32 v80, s38, v80
	v_lshrrev_b32_e32 v252, 2, v80
	v_and_b32_e32 v253, 0xf3, v252
	v_lshlrev_b32_e32 v252, 4, v80
	v_and_b32_e32 v252, 0x300, v252
	v_or_b32_e32 v253, v253, v252
	v_lshlrev_b32_e32 v252, 2, v80
	v_and_b32_e32 v252, 12, v252
	v_and_b32_e32 v80, 0xfffffc00, v80
	v_or3_b32 v80, v80, v253, v252
	v_add_u32_e32 v80, s38, v80
	v_lshrrev_b32_e32 v84, 8, v82
	global_store_byte v[80:81], v82, off offset:2
	global_store_byte v[80:81], v84, off offset:18
	global_store_byte_d16_hi v[80:81], v82, off offset:34
	v_lshrrev_b32_e32 v82, 24, v82
	global_store_byte v[80:81], v82, off offset:50
	global_store_byte v[80:81], v83, off offset:66
	v_lshrrev_b32_e32 v82, 8, v83
	global_store_byte v[80:81], v82, off offset:82
	global_store_byte_d16_hi v[80:81], v83, off offset:98
	v_lshrrev_b32_e32 v82, 24, v83
	global_store_byte v[80:81], v82, off offset:114
	s_mov_b64 s[86:87], 0

.LBB0_2330:
	s_waitcnt lgkmcnt(6)
	v_mov_b32_e32 v92, v202
	s_waitcnt lgkmcnt(4)
	v_mov_b32_e32 v93, v202
	v_pk_mul_f32 v[90:91], v[92:93], v[90:91]
	v_pk_mul_f32 v[88:89], v[202:203], v[88:89]
	v_pk_mul_f32 v[92:93], v[92:93], v[98:99]
	v_pk_mul_f32 v[94:95], v[202:203], v[96:97]
	s_and_b64 vcc, exec, s[12:13]
	s_mov_b64 s[84:85], -1
	s_cbranch_vccnz .LBB0_2342
	s_mov_b64 s[88:89], -1
	s_mov_b64 s[84:85], 0
	s_cmp_lt_i32 s80, 7
	s_mov_b64 s[86:87], 0
	s_cbranch_scc1 .LBB0_2337
	s_cmp_eq_u32 s80, 7
	s_mov_b64 s[86:87], -1
	s_cbranch_scc0 .LBB0_2334
	v_mov_b32_e32 v98, v171
	v_cvt_pk_fp8_f32 v98, v88, v89
	v_mov_b32_e32 v99, v171
	v_cvt_pk_fp8_f32 v99, v94, v95
	v_add_u32_e32 v96, s30, v136
	v_cvt_pk_fp8_f32 v98, v90, v91 op_sel:[0,0,1]
	v_ashrrev_i32_e32 v97, 31, v96
	v_cvt_pk_fp8_f32 v99, v92, v93 op_sel:[0,0,1]
	v_lshlrev_b64 v[96:97], 12, v[96:97]
	v_lshl_add_u64 v[96:97], v[186:187], 0, v[96:97]
	v_subrev_u32_e32 v96, s38, v96
	v_lshrrev_b32_e32 v252, 2, v96
	v_and_b32_e32 v253, 0xf3, v252
	v_lshlrev_b32_e32 v252, 4, v96
	v_and_b32_e32 v252, 0x300, v252
	v_or_b32_e32 v253, v253, v252
	v_lshlrev_b32_e32 v252, 2, v96
	v_and_b32_e32 v252, 12, v252
	v_and_b32_e32 v96, 0xfffffc00, v96
	v_or3_b32 v96, v96, v253, v252
	v_add_u32_e32 v96, s38, v96
	v_lshrrev_b32_e32 v100, 8, v98
	global_store_byte v[96:97], v98, off
	global_store_byte v[96:97], v100, off offset:16
	global_store_byte_d16_hi v[96:97], v98, off offset:32
	v_lshrrev_b32_e32 v98, 24, v98
	global_store_byte v[96:97], v98, off offset:48
	global_store_byte v[96:97], v99, off offset:64
	v_lshrrev_b32_e32 v98, 8, v99
	global_store_byte v[96:97], v98, off offset:80
	global_store_byte_d16_hi v[96:97], v99, off offset:96
	v_lshrrev_b32_e32 v98, 24, v99
	global_store_byte v[96:97], v98, off offset:112
	s_mov_b64 s[86:87], 0

.LBB0_2352:
	s_waitcnt vmcnt(3)
	v_mov_b32_e32 v72, v202
	v_mov_b32_e32 v73, v202
	v_pk_mul_f32 v[70:71], v[72:73], v[70:71]
	v_pk_mul_f32 v[68:69], v[202:203], v[68:69]
	v_pk_mul_f32 v[66:67], v[72:73], v[66:67]
	v_pk_mul_f32 v[64:65], v[202:203], v[64:65]
	s_and_b64 vcc, exec, s[12:13]
	s_mov_b64 s[10:11], -1
	s_cbranch_vccnz .LBB0_2364
	s_mov_b64 s[82:83], -1
	s_mov_b64 s[10:11], 0
	s_cmp_lt_i32 s80, 7
	s_mov_b64 s[12:13], 0
	s_cbranch_scc1 .LBB0_2359
	s_cmp_eq_u32 s80, 7
	s_mov_b64 s[12:13], -1
	s_cbranch_scc0 .LBB0_2356
	v_mov_b32_e32 v74, v171
	v_cvt_pk_fp8_f32 v74, v68, v69
	v_mov_b32_e32 v75, v171
	v_cvt_pk_fp8_f32 v75, v64, v65
	v_add_u32_e32 v72, s33, v136
	v_cvt_pk_fp8_f32 v74, v70, v71 op_sel:[0,0,1]
	v_ashrrev_i32_e32 v73, 31, v72
	v_cvt_pk_fp8_f32 v75, v66, v67 op_sel:[0,0,1]
	v_lshlrev_b64 v[72:73], 12, v[72:73]
	v_lshl_add_u64 v[72:73], v[188:189], 0, v[72:73]
	v_subrev_u32_e32 v72, s38, v72
	v_lshrrev_b32_e32 v252, 2, v72
	v_and_b32_e32 v253, 0xf3, v252
	v_lshlrev_b32_e32 v252, 4, v72
	v_and_b32_e32 v252, 0x300, v252
	v_or_b32_e32 v253, v253, v252
	v_lshlrev_b32_e32 v252, 2, v72
	v_and_b32_e32 v252, 12, v252
	v_and_b32_e32 v72, 0xfffffc00, v72
	v_or3_b32 v72, v72, v253, v252
	v_add_u32_e32 v72, s38, v72
	s_waitcnt vmcnt(1)
	v_lshrrev_b32_e32 v76, 8, v74
	global_store_byte v[72:73], v74, off
	global_store_byte v[72:73], v76, off offset:16
	global_store_byte_d16_hi v[72:73], v74, off offset:32
	v_lshrrev_b32_e32 v74, 24, v74
	global_store_byte v[72:73], v74, off offset:48
	global_store_byte v[72:73], v75, off offset:64
	v_lshrrev_b32_e32 v74, 8, v75
	global_store_byte v[72:73], v74, off offset:80
	global_store_byte_d16_hi v[72:73], v75, off offset:96
	v_lshrrev_b32_e32 v74, 24, v75
	global_store_byte v[72:73], v74, off offset:112
	s_mov_b64 s[12:13], 0

.LBB0_3923:
	s_lshl_b64 s[14:15], 1, s10
	s_or_b64 s[14:15], s[14:15], s[12:13]
	v_cmp_le_u64_e32 vcc, s[14:15], v[14:15]
	s_bcnt1_i32_b64 s16, vcc
	v_cmp_le_u64_e32 vcc, s[14:15], v[12:13]
	s_bcnt1_i32_b64 s17, vcc
	v_cmp_le_u64_e32 vcc, s[14:15], v[6:7]
	s_add_i32 s16, s17, s16
	s_bcnt1_i32_b64 s17, vcc
	v_cmp_le_u64_e32 vcc, s[14:15], v[4:5]
	s_add_i32 s16, s16, s17
	s_bcnt1_i32_b64 s17, vcc
	s_add_i32 s16, s16, s17
	s_cmp_gt_u32 s16, 15
	s_cselect_b32 s13, s15, s13
	s_cselect_b32 s12, s14, s12
	s_cmp_lg_u32 s16, 16
	s_cselect_b64 s[14:15], -1, 0
	s_cmp_lg_u32 s10, 0
	s_cselect_b64 s[16:17], -1, 0
	s_and_b64 s[14:15], s[14:15], s[16:17]
	s_add_u32 s10, s10, -1
	s_addc_u32 s11, s11, -1
	s_and_b64 vcc, exec, s[14:15]
	s_cbranch_vccnz .LBB0_3923
	v_cmp_le_u64_e32 vcc, s[12:13], v[14:15]
	s_nop 1
	v_and_b32_e32 v9, vcc_lo, v2
	v_and_b32_e32 v8, vcc_hi, v1
	v_bcnt_u32_b32 v9, v9, 0
	v_bcnt_u32_b32 v8, v8, v9
	v_mov_b32_e32 v9, v0
	v_cmp_gt_u64_e64 s[10:11], 16, v[8:9]
	s_and_b64 s[14:15], vcc, s[10:11]
	s_and_saveexec_b64 s[10:11], s[14:15]
	v_lshl_add_u32 v8, v8, 2, s61
	ds_write_b32 v8, v3
	s_or_b64 exec, exec, s[10:11]
	s_bcnt1_i32_b64 s14, vcc
	v_cmp_le_u64_e32 vcc, s[12:13], v[12:13]
	s_nop 1
	v_and_b32_e32 v8, vcc_lo, v2
	v_and_b32_e32 v3, vcc_hi, v1
	v_bcnt_u32_b32 v8, v8, 0
	v_bcnt_u32_b32 v3, v3, v8
	v_add_u32_e32 v3, s14, v3
	v_cmp_gt_u32_e64 s[10:11], 16, v3
	s_and_b64 s[16:17], vcc, s[10:11]
	s_and_saveexec_b64 s[10:11], s[16:17]
	v_lshl_add_u32 v3, v3, 2, s61
	ds_write_b32 v3, v11
	s_or_b64 exec, exec, s[10:11]
	s_bcnt1_i32_b64 s10, vcc
	v_cmp_le_u64_e32 vcc, s[12:13], v[6:7]
	s_add_i32 s14, s10, s14
	s_nop 0
	v_and_b32_e32 v6, vcc_lo, v2
	v_and_b32_e32 v3, vcc_hi, v1
	v_bcnt_u32_b32 v6, v6, 0
	v_bcnt_u32_b32 v3, v3, v6
	v_add_u32_e32 v3, s14, v3
	v_cmp_gt_u32_e64 s[10:11], 16, v3
	s_and_b64 s[16:17], vcc, s[10:11]
	s_and_saveexec_b64 s[10:11], s[16:17]
	v_lshl_add_u32 v3, v3, 2, s61
	ds_write_b32 v3, v20
	s_or_b64 exec, exec, s[10:11]
	s_bcnt1_i32_b64 s10, vcc
	v_cmp_le_u64_e32 vcc, s[12:13], v[4:5]
	s_add_i32 s14, s14, s10
	s_nop 0
	v_and_b32_e32 v2, vcc_lo, v2
	v_and_b32_e32 v1, vcc_hi, v1
	v_bcnt_u32_b32 v2, v2, 0
	v_bcnt_u32_b32 v1, v1, v2
	v_add_u32_e32 v1, s14, v1
	v_cmp_gt_u32_e64 s[10:11], 16, v1
	s_and_b64 s[12:13], vcc, s[10:11]
	s_and_saveexec_b64 s[10:11], s[12:13]
	v_lshl_add_u32 v1, v1, 2, s61
	ds_write_b32 v1, v21
	s_or_b64 exec, exec, s[10:11]
	v_cmp_gt_i32_e32 vcc, s6, v49
	v_mov_b32_e32 v1, s81
	v_mov_b32_e32 v2, s79
	v_cndmask_b32_e32 v3, v1, v2, vcc
	v_mov_b32_e32 v1, s80
	v_mov_b32_e32 v2, s78
	v_cndmask_b32_e32 v2, v1, v2, vcc
	v_and_b32_e32 v4, 0xff0, v124
	v_mov_b32_e32 v5, v0
	v_lshl_add_u64 v[6:7], v[2:3], 0, v[4:5]
	v_cndmask_b32_e64 v1, v174, 0, vcc
	v_mov_b32_e32 v2, s49
	s_movk_i32 s10, 0xfe
	v_add3_u32 v1, s6, v1, v4
	v_sub_u32_e64 v8, s10, v2 clamp
	global_load_dwordx4 v[2:5], v[6:7], off
	s_lshl_b32 s54, s48, 12
	s_mov_b32 s87, s55
	s_lshl_b64 s[12:13], s[86:87], 11
	s_add_u32 s10, s38, s12
	s_addc_u32 s11, s39, s13
	v_lshlrev_b32_e32 v10, 12, v8
	v_mov_b32_e32 v11, v0
	v_lshl_add_u64 v[10:11], v[6:7], 0, v[10:11]
	global_load_dwordx4 v[10:13], v[10:11], off
	v_lshl_add_u64 v[14:15], v[6:7], 0, s[54:55]
	global_load_dwordx4 v[14:17], v[14:15], off
	v_mov_b32_e32 v7, v0
	s_waitcnt vmcnt(2)
	ds_write_b128 v1, v[2:5]
	s_waitcnt vmcnt(1)
	ds_write_b128 v1, v[10:13] offset:8192
	s_waitcnt vmcnt(0)
	ds_write_b128 v1, v[14:17] offset:16384
	v_and_b32_e32 v4, 48, v49
	v_lshlrev_b32_e32 v2, 1, v121
	v_mov_b32_e32 v3, v0
	v_lshl_add_u64 v[2:3], s[10:11], 0, v[2:3]
	v_lshlrev_b32_e32 v6, 1, v4
	v_lshl_add_u64 v[6:7], v[2:3], 0, v[6:7]
	v_mov_b32_e32 v2, v0
	v_mov_b32_e32 v3, v0
	v_mov_b32_e32 v1, v0
	v_mov_b64_e32 v[72:73], v[2:3]
	v_cmp_gt_u32_e64 s[10:11], 4, v122
	v_mov_b64_e32 v[70:71], v[0:1]
	s_waitcnt lgkmcnt(0)
	s_barrier
	v_and_b32_e32 v1, 63, v160
	v_lshrrev_b32_e32 v203, 6, v160
	v_and_b32_e32 v201, 15, v1
	v_lshrrev_b32_e32 v187, 4, v1
	v_readfirstlane_b32 s22, v203
	v_and_b32_e32 v165, 3, v201
	v_lshrrev_b32_e32 v251, 2, v201
	v_mov_b32_e32 v193, 0
	v_lshlrev_b32_e32 v192, 4, v1
	v_lshl_add_u64 v[166:167], s[78:79], 0, v[192:193]
	v_lshl_add_u64 v[190:191], s[80:81], 0, v[192:193]
	v_add_u32_e32 v188, 0x100, v192
	v_mov_b32_e32 v199, 0xf149f2ca
	s_lshl_b32 s23, s22, 9
	s_add_i32 s23, s23, 0x20900
	v_lshl_add_u32 v203, v1, 2, s23
	ds_read_b32 v252, v203
	ds_read_b32 v253, v203 offset:256
	s_lshl_b32 s23, s22, 10
	s_add_i32 s23, s23, 0x10900
	v_mov_b32_e32 v244, 0
	v_mov_b32_e32 v245, 0
	v_mov_b32_e32 v246, 0
	v_mov_b32_e32 v247, 0
	v_lshl_add_u32 v250, v1, 4, s23
	ds_write_b128 v250, v[244:247]
	v_lshrrev_b32_e32 v248, 4, v1
	v_lshlrev_b32_e64 v249, v248, 1
	v_lshlrev_b32_e32 v250, 4, v249
	s_waitcnt lgkmcnt(0)
	v_cmp_le_i32_e32 vcc, 0, v252
	v_lshl_add_u32 v203, v252, 2, s23
	s_and_saveexec_b64 s[12:13], vcc
	ds_or_b32 v203, v249
	s_mov_b64 exec, s[12:13]
	v_cmp_le_i32_e32 vcc, 0, v253
	v_lshl_add_u32 v203, v253, 2, s23
	s_and_saveexec_b64 s[12:13], vcc
	ds_or_b32 v203, v250
	s_mov_b64 exec, s[12:13]
	v_lshl_add_u32 v203, v1, 2, s23
	s_waitcnt lgkmcnt(0)
	ds_read_b32 v244, v203
	ds_read_b32 v245, v203 offset:256
	ds_read_b32 v246, v203 offset:512
	ds_read_b32 v247, v203 offset:768
	s_lshl_b32 s23, s22, 12
	s_add_i32 s23, s23, 0x8900
	v_lshl_add_u32 v207, v165, 2, v251
	v_lshl_add_u32 v207, v207, 7, s23
	v_lshl_add_u32 v207, v187, 3, v207
	s_lshl_b32 s21, s22, 3
	s_add_i32 s20, s48, -1
	s_lshl_b32 s54, s48, 6
	s_add_i32 s54, s54, s21
	s_and_b32 s101, s65, 3
	s_lshl_b32 s12, s54, 11
	s_lshl_b32 s23, s101, 9
	s_add_i32 s12, s12, s23
	s_add_u32 s12, s38, s12
	s_addc_u32 s13, s39, 0
	v_lshlrev_b32_e32 v192, 7, v251
	v_lshl_or_b32 v192, v187, 5, v192
	v_lshl_or_b32 v192, v165, 11, v192
	v_lshl_add_u64 v[192:193], s[12:13], 0, v[192:193]
	global_load_dwordx4 v[212:215], v[192:193], off
	global_load_dwordx4 v[216:219], v[192:193], off offset:16
	v_add_co_u32_e32 v192, vcc, 0x2000, v192
	s_nop 1
	v_addc_co_u32_e32 v193, vcc, 0, v193, vcc
	global_load_dwordx4 v[220:223], v[192:193], off
	global_load_dwordx4 v[224:227], v[192:193], off offset:16
	s_mul_i32 s12, s54, 0xc0
	s_lshl_b32 s23, s101, 4
	s_add_i32 s12, s12, s23
	s_add_i32 s12, s12, 0xf400040
	s_add_u32 s12, s38, s12
	s_addc_u32 s13, s39, 0
	v_mul_u32_u24_e32 v248, 0xc0, v165
	v_mov_b32_e32 v249, 0
	v_lshl_add_u32 v248, v251, 2, v248
	v_lshl_add_u64 v[248:249], s[12:13], 0, v[248:249]
	global_load_dword v208, v[248:249], off
	global_load_dword v148, v[248:249], off offset:768
	v_lshlrev_b32_e32 v187, 4, v187
	v_lshl_add_u32 v187, v251, 6, v187
	v_lshl_add_u32 v187, v165, 2, v187
	s_mov_b32 s13, 0
	s_waitcnt lgkmcnt(0)
	v_lshl_or_b32 v164, v245, 8, v244
	v_lshl_or_b32 v164, v246, 16, v164
	v_lshl_or_b32 v164, v247, 24, v164
	v_and_b32_e32 v203, 0xff, v164
	v_cmp_ne_u32_e64 s[98:99], 0, v203
	s_mov_b32 s100, 0
	v_mov_b32_e32 v158, v199
	v_mov_b32_e32 v204, 0
	v_mov_b32_e32 v159, v199
	v_mov_b32_e32 v205, 0
	v_mov_b32_e32 v162, v199
	v_mov_b32_e32 v252, 0
	v_mov_b32_e32 v163, v199
	v_mov_b32_e32 v253, 0
	v_mov_b32_e32 v102, 0
	v_mov_b32_e32 v103, 0
	v_mov_b32_e32 v104, 0
	v_mov_b32_e32 v105, 0
	v_mov_b32_e32 v106, 0
	v_mov_b32_e32 v107, 0
	v_mov_b32_e32 v108, 0
	v_mov_b32_e32 v109, 0
	v_mov_b32_e32 v110, 0
	v_mov_b32_e32 v111, 0
	v_mov_b32_e32 v112, 0
	v_mov_b32_e32 v113, 0
	v_mov_b32_e32 v114, 0
	v_mov_b32_e32 v115, 0
	v_mov_b32_e32 v116, 0
	v_mov_b32_e32 v117, 0
	v_mov_b32_e32 v197, v199
	v_mov_b32_e32 v206, 0
	v_mov_b32_e32 v198, v199
	v_mov_b32_e32 v1, 0
	v_mov_b32_e32 v200, v199
	v_mov_b32_e32 v133, 0
	v_mov_b32_e32 v202, v199
	v_mov_b32_e32 v209, 0
	v_mov_b32_e32 v118, 0
	v_mov_b32_e32 v119, 0
	v_mov_b32_e32 v120, 0
	v_mov_b32_e32 v121, 0
	v_mov_b32_e32 v122, 0
	v_mov_b32_e32 v123, 0
	v_mov_b32_e32 v124, 0
	v_mov_b32_e32 v125, 0
	v_mov_b32_e32 v136, 0
	v_mov_b32_e32 v137, 0
	v_mov_b32_e32 v138, 0
	v_mov_b32_e32 v139, 0
	v_mov_b32_e32 v140, 0
	v_mov_b32_e32 v141, 0
	v_mov_b32_e32 v142, 0
	v_mov_b32_e32 v143, 0

.Lsb_wd_24:
	s_bfe_u32 s22, s17, 0x40000
	s_cmp_eq_u32 s22, 0
	s_cbranch_scc1 .Lsb_sg_25
	v_mfma_f32_16x16x32_fp8_fp8 v[66:69], v[144:145], v[2:3], 0
	v_mfma_f32_16x16x32_fp8_fp8 v[70:73], v[144:145], v[6:7], 0
	v_mfma_f32_16x16x32_fp8_fp8 v[74:77], v[144:145], v[10:11], 0
	v_mfma_f32_16x16x32_fp8_fp8 v[78:81], v[144:145], v[14:15], 0
	v_mfma_f32_16x16x32_fp8_fp8 v[66:69], v[146:147], v[4:5], v[66:69]
	v_mfma_f32_16x16x32_fp8_fp8 v[70:73], v[146:147], v[8:9], v[70:73]
	v_mfma_f32_16x16x32_fp8_fp8 v[74:77], v[146:147], v[12:13], v[74:77]
	v_mfma_f32_16x16x32_fp8_fp8 v[78:81], v[146:147], v[16:17], v[78:81]
	v_mov_b32_e32 v154, 0
	v_mov_b32_e32 v155, 0
	v_mov_b32_e32 v156, 0
	v_mov_b32_e32 v157, 0
	s_bfe_u32 s54, s17, 0x40000
	s_mov_b32 s22, 0x3e38aa3b
	s_cmp_lg_u32 s14, s48
	s_nop 3
	s_cbranch_scc1 .Lsb_nd_27
	s_add_i32 s23, s21, 0
	v_cmp_lt_i32_e32 vcc, s23, v201
	s_nop 1
	v_cndmask_b32_e32 v66, v66, v199, vcc
	s_add_i32 s23, s21, -16
	v_cmp_lt_i32_e32 vcc, s23, v201
	s_nop 1
	v_cndmask_b32_e32 v70, v70, v199, vcc
	s_add_i32 s23, s21, -32
	v_cmp_lt_i32_e32 vcc, s23, v201
	s_nop 1
	v_cndmask_b32_e32 v74, v74, v199, vcc
	s_add_i32 s23, s21, -48
	v_cmp_lt_i32_e32 vcc, s23, v201
	s_nop 1
	v_cndmask_b32_e32 v78, v78, v199, vcc
	s_add_i32 s23, s21, 1
	v_cmp_lt_i32_e32 vcc, s23, v201
	s_nop 1
	v_cndmask_b32_e32 v67, v67, v199, vcc
	s_add_i32 s23, s21, -15
	v_cmp_lt_i32_e32 vcc, s23, v201
	s_nop 1
	v_cndmask_b32_e32 v71, v71, v199, vcc
	s_add_i32 s23, s21, -31
	v_cmp_lt_i32_e32 vcc, s23, v201
	s_nop 1
	v_cndmask_b32_e32 v75, v75, v199, vcc
	s_add_i32 s23, s21, -47
	v_cmp_lt_i32_e32 vcc, s23, v201
	s_nop 1
	v_cndmask_b32_e32 v79, v79, v199, vcc
	s_add_i32 s23, s21, 2
	v_cmp_lt_i32_e32 vcc, s23, v201
	s_nop 1
	v_cndmask_b32_e32 v68, v68, v199, vcc
	s_add_i32 s23, s21, -14
	v_cmp_lt_i32_e32 vcc, s23, v201
	s_nop 1
	v_cndmask_b32_e32 v72, v72, v199, vcc
	s_add_i32 s23, s21, -30
	v_cmp_lt_i32_e32 vcc, s23, v201
	s_nop 1
	v_cndmask_b32_e32 v76, v76, v199, vcc
	s_add_i32 s23, s21, -46
	v_cmp_lt_i32_e32 vcc, s23, v201
	s_nop 1
	v_cndmask_b32_e32 v80, v80, v199, vcc
	s_add_i32 s23, s21, 3
	v_cmp_lt_i32_e32 vcc, s23, v201
	s_nop 1
	v_cndmask_b32_e32 v69, v69, v199, vcc
	s_add_i32 s23, s21, -13
	v_cmp_lt_i32_e32 vcc, s23, v201
	s_nop 1
	v_cndmask_b32_e32 v73, v73, v199, vcc
	s_add_i32 s23, s21, -29
	v_cmp_lt_i32_e32 vcc, s23, v201
	s_nop 1
	v_cndmask_b32_e32 v77, v77, v199, vcc
	s_add_i32 s23, s21, -45
	v_cmp_lt_i32_e32 vcc, s23, v201
	s_nop 1
	v_cndmask_b32_e32 v81, v81, v199, vcc
.Lsb_nd_27:
	s_bitcmp1_b32 s54, 0
	s_cbranch_scc0 .Lsb_qs_28
	v_fma_f32 v244, v66, s22, -v158
	v_fma_f32 v245, v70, s22, -v158
	v_fma_f32 v246, v74, s22, -v158
	v_fma_f32 v247, v78, s22, -v158
	v_exp_f32_e32 v244, v244
	v_exp_f32_e32 v245, v245
	v_exp_f32_e32 v246, v246
	v_exp_f32_e32 v247, v247
	v_add_f32_e32 v248, v244, v245
	v_add_f32_e32 v249, v246, v247
	v_cvt_pk_fp8_f32 v250, v244, v245
	v_add_f32_e32 v248, v248, v249
	v_cvt_pk_fp8_f32 v250, v246, v247 op_sel:[0,0,1]
	v_cmp_lt_f32_e32 vcc, 0x43800000, v248
	s_nop 0
	s_cbranch_vccnz .Lsb_sl_29
.Lsb_bk_30:
	v_cmp_eq_u32_e32 vcc, 0, v165
	v_add_f32_e32 v204, v204, v248
	v_mov_b32_dpp v244, v250 quad_perm:[0,0,0,0] row_mask:0xf bank_mask:0xf
	v_mov_b32_dpp v245, v250 quad_perm:[1,1,1,1] row_mask:0xf bank_mask:0xf
	v_mov_b32_dpp v246, v250 quad_perm:[2,2,2,2] row_mask:0xf bank_mask:0xf
	v_mov_b32_dpp v247, v250 quad_perm:[3,3,3,3] row_mask:0xf bank_mask:0xf
	v_cndmask_b32_e32 v154, v154, v244, vcc
	v_cndmask_b32_e32 v155, v155, v245, vcc
	v_cndmask_b32_e32 v156, v156, v246, vcc
	v_cndmask_b32_e32 v157, v157, v247, vcc
	s_branch .Lsb_qs_28
.Lsb_sl_29:
	v_max3_f32 v244, v66, v70, v74
	v_cmp_eq_u32_e32 vcc, 0, v165
	v_max_f32_e32 v244, v244, v78
	s_nop 1
	v_max_f32_dpp v244, v244, v244 quad_perm:[1,0,3,2] row_mask:0xf bank_mask:0xf
	s_nop 1
	v_max_f32_dpp v244, v244, v244 quad_perm:[2,3,0,1] row_mask:0xf bank_mask:0xf
	s_nop 1
	v_max_f32_dpp v244, v244, v244 row_half_mirror row_mask:0xf bank_mask:0xf
	s_nop 1
	v_max_f32_dpp v244, v244, v244 row_mirror row_mask:0xf bank_mask:0xf
	v_mul_f32_e32 v244, 0x3e38aa3b, v244
	v_max_f32_e32 v244, v158, v244
	v_sub_f32_e32 v245, v158, v244
	v_exp_f32_e32 v245, v245
	v_mov_b32_e32 v158, v244
	s_nop 0
	v_mul_f32_e32 v204, v204, v245
	v_cndmask_b32_e64 v246, 1.0, v245, vcc
	ds_bpermute_b32 v246, v187, v246
	s_waitcnt lgkmcnt(0)
	v_mul_f32_e32 v102, v102, v246
	v_mul_f32_e32 v103, v103, v246
	v_mul_f32_e32 v104, v104, v246
	v_mul_f32_e32 v105, v105, v246
	v_mul_f32_e32 v106, v106, v246
	v_mul_f32_e32 v107, v107, v246
	v_mul_f32_e32 v108, v108, v246
	v_mul_f32_e32 v109, v109, v246
	v_mul_f32_e32 v110, v110, v246
	v_mul_f32_e32 v111, v111, v246
	v_mul_f32_e32 v112, v112, v246
	v_mul_f32_e32 v113, v113, v246
	v_mul_f32_e32 v114, v114, v246
	v_mul_f32_e32 v115, v115, v246
	v_mul_f32_e32 v116, v116, v246
	v_mul_f32_e32 v117, v117, v246
	v_fma_f32 v244, v66, s22, -v158
	v_fma_f32 v245, v70, s22, -v158
	v_fma_f32 v246, v74, s22, -v158
	v_fma_f32 v247, v78, s22, -v158
	v_exp_f32_e32 v244, v244
	v_exp_f32_e32 v245, v245
	v_exp_f32_e32 v246, v246
	v_exp_f32_e32 v247, v247
	v_add_f32_e32 v248, v244, v245
	v_add_f32_e32 v249, v246, v247
	v_cvt_pk_fp8_f32 v250, v244, v245
	v_add_f32_e32 v248, v248, v249
	v_cvt_pk_fp8_f32 v250, v246, v247 op_sel:[0,0,1]
	s_nop 0
	s_branch .Lsb_bk_30
.Lsb_qs_28:
	s_bitcmp1_b32 s54, 1
	s_cbranch_scc0 .Lsb_qs_31
	v_fma_f32 v244, v67, s22, -v159
	v_fma_f32 v245, v71, s22, -v159
	v_fma_f32 v246, v75, s22, -v159
	v_fma_f32 v247, v79, s22, -v159
	v_exp_f32_e32 v244, v244
	v_exp_f32_e32 v245, v245
	v_exp_f32_e32 v246, v246
	v_exp_f32_e32 v247, v247
	v_add_f32_e32 v248, v244, v245
	v_add_f32_e32 v249, v246, v247
	v_cvt_pk_fp8_f32 v250, v244, v245
	v_add_f32_e32 v248, v248, v249
	v_cvt_pk_fp8_f32 v250, v246, v247 op_sel:[0,0,1]
	v_cmp_lt_f32_e32 vcc, 0x43800000, v248
	s_nop 0
	s_cbranch_vccnz .Lsb_sl_32
.Lsb_bk_33:
	v_cmp_eq_u32_e32 vcc, 1, v165
	v_add_f32_e32 v205, v205, v248
	v_mov_b32_dpp v244, v250 quad_perm:[0,0,0,0] row_mask:0xf bank_mask:0xf
	v_mov_b32_dpp v245, v250 quad_perm:[1,1,1,1] row_mask:0xf bank_mask:0xf
	v_mov_b32_dpp v246, v250 quad_perm:[2,2,2,2] row_mask:0xf bank_mask:0xf
	v_mov_b32_dpp v247, v250 quad_perm:[3,3,3,3] row_mask:0xf bank_mask:0xf
	v_cndmask_b32_e32 v154, v154, v244, vcc
	v_cndmask_b32_e32 v155, v155, v245, vcc
	v_cndmask_b32_e32 v156, v156, v246, vcc
	v_cndmask_b32_e32 v157, v157, v247, vcc
	s_branch .Lsb_qs_31
.Lsb_sl_32:
	v_max3_f32 v244, v67, v71, v75
	v_cmp_eq_u32_e32 vcc, 1, v165
	v_max_f32_e32 v244, v244, v79
	s_nop 1
	v_max_f32_dpp v244, v244, v244 quad_perm:[1,0,3,2] row_mask:0xf bank_mask:0xf
	s_nop 1
	v_max_f32_dpp v244, v244, v244 quad_perm:[2,3,0,1] row_mask:0xf bank_mask:0xf
	s_nop 1
	v_max_f32_dpp v244, v244, v244 row_half_mirror row_mask:0xf bank_mask:0xf
	s_nop 1
	v_max_f32_dpp v244, v244, v244 row_mirror row_mask:0xf bank_mask:0xf
	v_mul_f32_e32 v244, 0x3e38aa3b, v244
	v_max_f32_e32 v244, v159, v244
	v_sub_f32_e32 v245, v159, v244
	v_exp_f32_e32 v245, v245
	v_mov_b32_e32 v159, v244
	s_nop 0
	v_mul_f32_e32 v205, v205, v245
	v_cndmask_b32_e64 v246, 1.0, v245, vcc
	ds_bpermute_b32 v246, v187, v246
	s_waitcnt lgkmcnt(0)
	v_mul_f32_e32 v102, v102, v246
	v_mul_f32_e32 v103, v103, v246
	v_mul_f32_e32 v104, v104, v246
	v_mul_f32_e32 v105, v105, v246
	v_mul_f32_e32 v106, v106, v246
	v_mul_f32_e32 v107, v107, v246
	v_mul_f32_e32 v108, v108, v246
	v_mul_f32_e32 v109, v109, v246
	v_mul_f32_e32 v110, v110, v246
	v_mul_f32_e32 v111, v111, v246
	v_mul_f32_e32 v112, v112, v246
	v_mul_f32_e32 v113, v113, v246
	v_mul_f32_e32 v114, v114, v246
	v_mul_f32_e32 v115, v115, v246
	v_mul_f32_e32 v116, v116, v246
	v_mul_f32_e32 v117, v117, v246
	v_fma_f32 v244, v67, s22, -v159
	v_fma_f32 v245, v71, s22, -v159
	v_fma_f32 v246, v75, s22, -v159
	v_fma_f32 v247, v79, s22, -v159
	v_exp_f32_e32 v244, v244
	v_exp_f32_e32 v245, v245
	v_exp_f32_e32 v246, v246
	v_exp_f32_e32 v247, v247
	v_add_f32_e32 v248, v244, v245
	v_add_f32_e32 v249, v246, v247
	v_cvt_pk_fp8_f32 v250, v244, v245
	v_add_f32_e32 v248, v248, v249
	v_cvt_pk_fp8_f32 v250, v246, v247 op_sel:[0,0,1]
	s_nop 0
	s_branch .Lsb_bk_33
.Lsb_qs_31:
	s_bitcmp1_b32 s54, 2
	s_cbranch_scc0 .Lsb_qs_34
	v_fma_f32 v244, v68, s22, -v162
	v_fma_f32 v245, v72, s22, -v162
	v_fma_f32 v246, v76, s22, -v162
	v_fma_f32 v247, v80, s22, -v162
	v_exp_f32_e32 v244, v244
	v_exp_f32_e32 v245, v245
	v_exp_f32_e32 v246, v246
	v_exp_f32_e32 v247, v247
	v_add_f32_e32 v248, v244, v245
	v_add_f32_e32 v249, v246, v247
	v_cvt_pk_fp8_f32 v250, v244, v245
	v_add_f32_e32 v248, v248, v249
	v_cvt_pk_fp8_f32 v250, v246, v247 op_sel:[0,0,1]
	v_cmp_lt_f32_e32 vcc, 0x43800000, v248
	s_nop 0
	s_cbranch_vccnz .Lsb_sl_35
.Lsb_bk_36:
	v_cmp_eq_u32_e32 vcc, 2, v165
	v_add_f32_e32 v252, v252, v248
	v_mov_b32_dpp v244, v250 quad_perm:[0,0,0,0] row_mask:0xf bank_mask:0xf
	v_mov_b32_dpp v245, v250 quad_perm:[1,1,1,1] row_mask:0xf bank_mask:0xf
	v_mov_b32_dpp v246, v250 quad_perm:[2,2,2,2] row_mask:0xf bank_mask:0xf
	v_mov_b32_dpp v247, v250 quad_perm:[3,3,3,3] row_mask:0xf bank_mask:0xf
	v_cndmask_b32_e32 v154, v154, v244, vcc
	v_cndmask_b32_e32 v155, v155, v245, vcc
	v_cndmask_b32_e32 v156, v156, v246, vcc
	v_cndmask_b32_e32 v157, v157, v247, vcc
	s_branch .Lsb_qs_34
.Lsb_sl_35:
	v_max3_f32 v244, v68, v72, v76
	v_cmp_eq_u32_e32 vcc, 2, v165
	v_max_f32_e32 v244, v244, v80
	s_nop 1
	v_max_f32_dpp v244, v244, v244 quad_perm:[1,0,3,2] row_mask:0xf bank_mask:0xf
	s_nop 1
	v_max_f32_dpp v244, v244, v244 quad_perm:[2,3,0,1] row_mask:0xf bank_mask:0xf
	s_nop 1
	v_max_f32_dpp v244, v244, v244 row_half_mirror row_mask:0xf bank_mask:0xf
	s_nop 1
	v_max_f32_dpp v244, v244, v244 row_mirror row_mask:0xf bank_mask:0xf
	v_mul_f32_e32 v244, 0x3e38aa3b, v244
	v_max_f32_e32 v244, v162, v244
	v_sub_f32_e32 v245, v162, v244
	v_exp_f32_e32 v245, v245
	v_mov_b32_e32 v162, v244
	s_nop 0
	v_mul_f32_e32 v252, v252, v245
	v_cndmask_b32_e64 v246, 1.0, v245, vcc
	ds_bpermute_b32 v246, v187, v246
	s_waitcnt lgkmcnt(0)
	v_mul_f32_e32 v102, v102, v246
	v_mul_f32_e32 v103, v103, v246
	v_mul_f32_e32 v104, v104, v246
	v_mul_f32_e32 v105, v105, v246
	v_mul_f32_e32 v106, v106, v246
	v_mul_f32_e32 v107, v107, v246
	v_mul_f32_e32 v108, v108, v246
	v_mul_f32_e32 v109, v109, v246
	v_mul_f32_e32 v110, v110, v246
	v_mul_f32_e32 v111, v111, v246
	v_mul_f32_e32 v112, v112, v246
	v_mul_f32_e32 v113, v113, v246
	v_mul_f32_e32 v114, v114, v246
	v_mul_f32_e32 v115, v115, v246
	v_mul_f32_e32 v116, v116, v246
	v_mul_f32_e32 v117, v117, v246
	v_fma_f32 v244, v68, s22, -v162
	v_fma_f32 v245, v72, s22, -v162
	v_fma_f32 v246, v76, s22, -v162
	v_fma_f32 v247, v80, s22, -v162
	v_exp_f32_e32 v244, v244
	v_exp_f32_e32 v245, v245
	v_exp_f32_e32 v246, v246
	v_exp_f32_e32 v247, v247
	v_add_f32_e32 v248, v244, v245
	v_add_f32_e32 v249, v246, v247
	v_cvt_pk_fp8_f32 v250, v244, v245
	v_add_f32_e32 v248, v248, v249
	v_cvt_pk_fp8_f32 v250, v246, v247 op_sel:[0,0,1]
	s_nop 0
	s_branch .Lsb_bk_36
.Lsb_qs_34:
	s_bitcmp1_b32 s54, 3
	s_cbranch_scc0 .Lsb_qs_37
	v_fma_f32 v244, v69, s22, -v163
	v_fma_f32 v245, v73, s22, -v163
	v_fma_f32 v246, v77, s22, -v163
	v_fma_f32 v247, v81, s22, -v163
	v_exp_f32_e32 v244, v244
	v_exp_f32_e32 v245, v245
	v_exp_f32_e32 v246, v246
	v_exp_f32_e32 v247, v247
	v_add_f32_e32 v248, v244, v245
	v_add_f32_e32 v249, v246, v247
	v_cvt_pk_fp8_f32 v250, v244, v245
	v_add_f32_e32 v248, v248, v249
	v_cvt_pk_fp8_f32 v250, v246, v247 op_sel:[0,0,1]
	v_cmp_lt_f32_e32 vcc, 0x43800000, v248
	s_nop 0
	s_cbranch_vccnz .Lsb_sl_38
.Lsb_bk_39:
	v_cmp_eq_u32_e32 vcc, 3, v165
	v_add_f32_e32 v253, v253, v248
	v_mov_b32_dpp v244, v250 quad_perm:[0,0,0,0] row_mask:0xf bank_mask:0xf
	v_mov_b32_dpp v245, v250 quad_perm:[1,1,1,1] row_mask:0xf bank_mask:0xf
	v_mov_b32_dpp v246, v250 quad_perm:[2,2,2,2] row_mask:0xf bank_mask:0xf
	v_mov_b32_dpp v247, v250 quad_perm:[3,3,3,3] row_mask:0xf bank_mask:0xf
	v_cndmask_b32_e32 v154, v154, v244, vcc
	v_cndmask_b32_e32 v155, v155, v245, vcc
	v_cndmask_b32_e32 v156, v156, v246, vcc
	v_cndmask_b32_e32 v157, v157, v247, vcc
	s_branch .Lsb_qs_37
.Lsb_sl_38:
	v_max3_f32 v244, v69, v73, v77
	v_cmp_eq_u32_e32 vcc, 3, v165
	v_max_f32_e32 v244, v244, v81
	s_nop 1
	v_max_f32_dpp v244, v244, v244 quad_perm:[1,0,3,2] row_mask:0xf bank_mask:0xf
	s_nop 1
	v_max_f32_dpp v244, v244, v244 quad_perm:[2,3,0,1] row_mask:0xf bank_mask:0xf
	s_nop 1
	v_max_f32_dpp v244, v244, v244 row_half_mirror row_mask:0xf bank_mask:0xf
	s_nop 1
	v_max_f32_dpp v244, v244, v244 row_mirror row_mask:0xf bank_mask:0xf
	v_mul_f32_e32 v244, 0x3e38aa3b, v244
	v_max_f32_e32 v244, v163, v244
	v_sub_f32_e32 v245, v163, v244
	v_exp_f32_e32 v245, v245
	v_mov_b32_e32 v163, v244
	s_nop 0
	v_mul_f32_e32 v253, v253, v245
	v_cndmask_b32_e64 v246, 1.0, v245, vcc
	ds_bpermute_b32 v246, v187, v246
	s_waitcnt lgkmcnt(0)
	v_mul_f32_e32 v102, v102, v246
	v_mul_f32_e32 v103, v103, v246
	v_mul_f32_e32 v104, v104, v246
	v_mul_f32_e32 v105, v105, v246
	v_mul_f32_e32 v106, v106, v246
	v_mul_f32_e32 v107, v107, v246
	v_mul_f32_e32 v108, v108, v246
	v_mul_f32_e32 v109, v109, v246
	v_mul_f32_e32 v110, v110, v246
	v_mul_f32_e32 v111, v111, v246
	v_mul_f32_e32 v112, v112, v246
	v_mul_f32_e32 v113, v113, v246
	v_mul_f32_e32 v114, v114, v246
	v_mul_f32_e32 v115, v115, v246
	v_mul_f32_e32 v116, v116, v246
	v_mul_f32_e32 v117, v117, v246
	v_fma_f32 v244, v69, s22, -v163
	v_fma_f32 v245, v73, s22, -v163
	v_fma_f32 v246, v77, s22, -v163
	v_fma_f32 v247, v81, s22, -v163
	v_exp_f32_e32 v244, v244
	v_exp_f32_e32 v245, v245
	v_exp_f32_e32 v246, v246
	v_exp_f32_e32 v247, v247
	v_add_f32_e32 v248, v244, v245
	v_add_f32_e32 v249, v246, v247
	v_cvt_pk_fp8_f32 v250, v244, v245
	v_add_f32_e32 v248, v248, v249
	v_cvt_pk_fp8_f32 v250, v246, v247 op_sel:[0,0,1]
	s_nop 0
	s_branch .Lsb_bk_39
.Lsb_qs_37:
	ds_bpermute_b32 v154, v187, v154
	ds_bpermute_b32 v155, v187, v155
	ds_bpermute_b32 v156, v187, v156
	ds_bpermute_b32 v157, v187, v157
	s_waitcnt lgkmcnt(0)
	v_mfma_f32_16x16x32_fp8_fp8 v[102:105], v[18:19], v[154:155], v[102:105]
	v_mfma_f32_16x16x32_fp8_fp8 v[106:109], v[22:23], v[154:155], v[106:109]
	v_mfma_f32_16x16x32_fp8_fp8 v[110:113], v[26:27], v[154:155], v[110:113]
	v_mfma_f32_16x16x32_fp8_fp8 v[114:117], v[30:31], v[154:155], v[114:117]
	v_mfma_f32_16x16x32_fp8_fp8 v[102:105], v[20:21], v[156:157], v[102:105]
	v_mfma_f32_16x16x32_fp8_fp8 v[106:109], v[24:25], v[156:157], v[106:109]
	v_mfma_f32_16x16x32_fp8_fp8 v[110:113], v[28:29], v[156:157], v[110:113]
	v_mfma_f32_16x16x32_fp8_fp8 v[114:117], v[32:33], v[156:157], v[114:117]
.Lsb_ce_26:
.Lsb_sg_25:
	s_bfe_u32 s22, s17, 0x40004
	s_cmp_eq_u32 s22, 0
	s_cbranch_scc1 .Lsb_sg_40
	v_mfma_f32_16x16x32_fp8_fp8 v[66:69], v[150:151], v[2:3], 0
	v_mfma_f32_16x16x32_fp8_fp8 v[70:73], v[150:151], v[6:7], 0
	v_mfma_f32_16x16x32_fp8_fp8 v[74:77], v[150:151], v[10:11], 0
	v_mfma_f32_16x16x32_fp8_fp8 v[78:81], v[150:151], v[14:15], 0
	v_mfma_f32_16x16x32_fp8_fp8 v[66:69], v[152:153], v[4:5], v[66:69]
	v_mfma_f32_16x16x32_fp8_fp8 v[70:73], v[152:153], v[8:9], v[70:73]
	v_mfma_f32_16x16x32_fp8_fp8 v[74:77], v[152:153], v[12:13], v[74:77]
	v_mfma_f32_16x16x32_fp8_fp8 v[78:81], v[152:153], v[16:17], v[78:81]
	v_mov_b32_e32 v154, 0
	v_mov_b32_e32 v155, 0
	v_mov_b32_e32 v156, 0
	v_mov_b32_e32 v157, 0
	s_bfe_u32 s54, s17, 0x40004
	s_mov_b32 s22, 0x3e38aa3b
	s_cmp_lg_u32 s14, s48
	s_nop 3
	s_cbranch_scc1 .Lsb_nd_42
	s_add_i32 s23, s21, 4
	v_cmp_lt_i32_e32 vcc, s23, v201
	s_nop 1
	v_cndmask_b32_e32 v66, v66, v199, vcc
	s_add_i32 s23, s21, -12
	v_cmp_lt_i32_e32 vcc, s23, v201
	s_nop 1
	v_cndmask_b32_e32 v70, v70, v199, vcc
	s_add_i32 s23, s21, -28
	v_cmp_lt_i32_e32 vcc, s23, v201
	s_nop 1
	v_cndmask_b32_e32 v74, v74, v199, vcc
	s_add_i32 s23, s21, -44
	v_cmp_lt_i32_e32 vcc, s23, v201
	s_nop 1
	v_cndmask_b32_e32 v78, v78, v199, vcc
	s_add_i32 s23, s21, 5
	v_cmp_lt_i32_e32 vcc, s23, v201
	s_nop 1
	v_cndmask_b32_e32 v67, v67, v199, vcc
	s_add_i32 s23, s21, -11
	v_cmp_lt_i32_e32 vcc, s23, v201
	s_nop 1
	v_cndmask_b32_e32 v71, v71, v199, vcc
	s_add_i32 s23, s21, -27
	v_cmp_lt_i32_e32 vcc, s23, v201
	s_nop 1
	v_cndmask_b32_e32 v75, v75, v199, vcc
	s_add_i32 s23, s21, -43
	v_cmp_lt_i32_e32 vcc, s23, v201
	s_nop 1
	v_cndmask_b32_e32 v79, v79, v199, vcc
	s_add_i32 s23, s21, 6
	v_cmp_lt_i32_e32 vcc, s23, v201
	s_nop 1
	v_cndmask_b32_e32 v68, v68, v199, vcc
	s_add_i32 s23, s21, -10
	v_cmp_lt_i32_e32 vcc, s23, v201
	s_nop 1
	v_cndmask_b32_e32 v72, v72, v199, vcc
	s_add_i32 s23, s21, -26
	v_cmp_lt_i32_e32 vcc, s23, v201
	s_nop 1
	v_cndmask_b32_e32 v76, v76, v199, vcc
	s_add_i32 s23, s21, -42
	v_cmp_lt_i32_e32 vcc, s23, v201
	s_nop 1
	v_cndmask_b32_e32 v80, v80, v199, vcc
	s_add_i32 s23, s21, 7
	v_cmp_lt_i32_e32 vcc, s23, v201
	s_nop 1
	v_cndmask_b32_e32 v69, v69, v199, vcc
	s_add_i32 s23, s21, -9
	v_cmp_lt_i32_e32 vcc, s23, v201
	s_nop 1
	v_cndmask_b32_e32 v73, v73, v199, vcc
	s_add_i32 s23, s21, -25
	v_cmp_lt_i32_e32 vcc, s23, v201
	s_nop 1
	v_cndmask_b32_e32 v77, v77, v199, vcc
	s_add_i32 s23, s21, -41
	v_cmp_lt_i32_e32 vcc, s23, v201
	s_nop 1
	v_cndmask_b32_e32 v81, v81, v199, vcc
.Lsb_nd_42:
	s_bitcmp1_b32 s54, 0
	s_cbranch_scc0 .Lsb_qs_43
	v_fma_f32 v244, v66, s22, -v197
	v_fma_f32 v245, v70, s22, -v197
	v_fma_f32 v246, v74, s22, -v197
	v_fma_f32 v247, v78, s22, -v197
	v_exp_f32_e32 v244, v244
	v_exp_f32_e32 v245, v245
	v_exp_f32_e32 v246, v246
	v_exp_f32_e32 v247, v247
	v_add_f32_e32 v248, v244, v245
	v_add_f32_e32 v249, v246, v247
	v_cvt_pk_fp8_f32 v250, v244, v245
	v_add_f32_e32 v248, v248, v249
	v_cvt_pk_fp8_f32 v250, v246, v247 op_sel:[0,0,1]
	v_cmp_lt_f32_e32 vcc, 0x43800000, v248
	s_nop 0
	s_cbranch_vccnz .Lsb_sl_44
.Lsb_bk_45:
	v_cmp_eq_u32_e32 vcc, 0, v165
	v_add_f32_e32 v206, v206, v248
	v_mov_b32_dpp v244, v250 quad_perm:[0,0,0,0] row_mask:0xf bank_mask:0xf
	v_mov_b32_dpp v245, v250 quad_perm:[1,1,1,1] row_mask:0xf bank_mask:0xf
	v_mov_b32_dpp v246, v250 quad_perm:[2,2,2,2] row_mask:0xf bank_mask:0xf
	v_mov_b32_dpp v247, v250 quad_perm:[3,3,3,3] row_mask:0xf bank_mask:0xf
	v_cndmask_b32_e32 v154, v154, v244, vcc
	v_cndmask_b32_e32 v155, v155, v245, vcc
	v_cndmask_b32_e32 v156, v156, v246, vcc
	v_cndmask_b32_e32 v157, v157, v247, vcc
	s_branch .Lsb_qs_43
.Lsb_sl_44:
	v_max3_f32 v244, v66, v70, v74
	v_cmp_eq_u32_e32 vcc, 0, v165
	v_max_f32_e32 v244, v244, v78
	s_nop 1
	v_max_f32_dpp v244, v244, v244 quad_perm:[1,0,3,2] row_mask:0xf bank_mask:0xf
	s_nop 1
	v_max_f32_dpp v244, v244, v244 quad_perm:[2,3,0,1] row_mask:0xf bank_mask:0xf
	s_nop 1
	v_max_f32_dpp v244, v244, v244 row_half_mirror row_mask:0xf bank_mask:0xf
	s_nop 1
	v_max_f32_dpp v244, v244, v244 row_mirror row_mask:0xf bank_mask:0xf
	v_mul_f32_e32 v244, 0x3e38aa3b, v244
	v_max_f32_e32 v244, v197, v244
	v_sub_f32_e32 v245, v197, v244
	v_exp_f32_e32 v245, v245
	v_mov_b32_e32 v197, v244
	s_nop 0
	v_mul_f32_e32 v206, v206, v245
	v_cndmask_b32_e64 v246, 1.0, v245, vcc
	ds_bpermute_b32 v246, v187, v246
	s_waitcnt lgkmcnt(0)
	v_mul_f32_e32 v118, v118, v246
	v_mul_f32_e32 v119, v119, v246
	v_mul_f32_e32 v120, v120, v246
	v_mul_f32_e32 v121, v121, v246
	v_mul_f32_e32 v122, v122, v246
	v_mul_f32_e32 v123, v123, v246
	v_mul_f32_e32 v124, v124, v246
	v_mul_f32_e32 v125, v125, v246
	v_mul_f32_e32 v136, v136, v246
	v_mul_f32_e32 v137, v137, v246
	v_mul_f32_e32 v138, v138, v246
	v_mul_f32_e32 v139, v139, v246
	v_mul_f32_e32 v140, v140, v246
	v_mul_f32_e32 v141, v141, v246
	v_mul_f32_e32 v142, v142, v246
	v_mul_f32_e32 v143, v143, v246
	v_fma_f32 v244, v66, s22, -v197
	v_fma_f32 v245, v70, s22, -v197
	v_fma_f32 v246, v74, s22, -v197
	v_fma_f32 v247, v78, s22, -v197
	v_exp_f32_e32 v244, v244
	v_exp_f32_e32 v245, v245
	v_exp_f32_e32 v246, v246
	v_exp_f32_e32 v247, v247
	v_add_f32_e32 v248, v244, v245
	v_add_f32_e32 v249, v246, v247
	v_cvt_pk_fp8_f32 v250, v244, v245
	v_add_f32_e32 v248, v248, v249
	v_cvt_pk_fp8_f32 v250, v246, v247 op_sel:[0,0,1]
	s_nop 0
	s_branch .Lsb_bk_45
.Lsb_qs_43:
	s_bitcmp1_b32 s54, 1
	s_cbranch_scc0 .Lsb_qs_46
	v_fma_f32 v244, v67, s22, -v198
	v_fma_f32 v245, v71, s22, -v198
	v_fma_f32 v246, v75, s22, -v198
	v_fma_f32 v247, v79, s22, -v198
	v_exp_f32_e32 v244, v244
	v_exp_f32_e32 v245, v245
	v_exp_f32_e32 v246, v246
	v_exp_f32_e32 v247, v247
	v_add_f32_e32 v248, v244, v245
	v_add_f32_e32 v249, v246, v247
	v_cvt_pk_fp8_f32 v250, v244, v245
	v_add_f32_e32 v248, v248, v249
	v_cvt_pk_fp8_f32 v250, v246, v247 op_sel:[0,0,1]
	v_cmp_lt_f32_e32 vcc, 0x43800000, v248
	s_nop 0
	s_cbranch_vccnz .Lsb_sl_47
.Lsb_bk_48:
	v_cmp_eq_u32_e32 vcc, 1, v165
	v_add_f32_e32 v1, v1, v248
	v_mov_b32_dpp v244, v250 quad_perm:[0,0,0,0] row_mask:0xf bank_mask:0xf
	v_mov_b32_dpp v245, v250 quad_perm:[1,1,1,1] row_mask:0xf bank_mask:0xf
	v_mov_b32_dpp v246, v250 quad_perm:[2,2,2,2] row_mask:0xf bank_mask:0xf
	v_mov_b32_dpp v247, v250 quad_perm:[3,3,3,3] row_mask:0xf bank_mask:0xf
	v_cndmask_b32_e32 v154, v154, v244, vcc
	v_cndmask_b32_e32 v155, v155, v245, vcc
	v_cndmask_b32_e32 v156, v156, v246, vcc
	v_cndmask_b32_e32 v157, v157, v247, vcc
	s_branch .Lsb_qs_46
.Lsb_sl_47:
	v_max3_f32 v244, v67, v71, v75
	v_cmp_eq_u32_e32 vcc, 1, v165
	v_max_f32_e32 v244, v244, v79
	s_nop 1
	v_max_f32_dpp v244, v244, v244 quad_perm:[1,0,3,2] row_mask:0xf bank_mask:0xf
	s_nop 1
	v_max_f32_dpp v244, v244, v244 quad_perm:[2,3,0,1] row_mask:0xf bank_mask:0xf
	s_nop 1
	v_max_f32_dpp v244, v244, v244 row_half_mirror row_mask:0xf bank_mask:0xf
	s_nop 1
	v_max_f32_dpp v244, v244, v244 row_mirror row_mask:0xf bank_mask:0xf
	v_mul_f32_e32 v244, 0x3e38aa3b, v244
	v_max_f32_e32 v244, v198, v244
	v_sub_f32_e32 v245, v198, v244
	v_exp_f32_e32 v245, v245
	v_mov_b32_e32 v198, v244
	s_nop 0
	v_mul_f32_e32 v1, v1, v245
	v_cndmask_b32_e64 v246, 1.0, v245, vcc
	ds_bpermute_b32 v246, v187, v246
	s_waitcnt lgkmcnt(0)
	v_mul_f32_e32 v118, v118, v246
	v_mul_f32_e32 v119, v119, v246
	v_mul_f32_e32 v120, v120, v246
	v_mul_f32_e32 v121, v121, v246
	v_mul_f32_e32 v122, v122, v246
	v_mul_f32_e32 v123, v123, v246
	v_mul_f32_e32 v124, v124, v246
	v_mul_f32_e32 v125, v125, v246
	v_mul_f32_e32 v136, v136, v246
	v_mul_f32_e32 v137, v137, v246
	v_mul_f32_e32 v138, v138, v246
	v_mul_f32_e32 v139, v139, v246
	v_mul_f32_e32 v140, v140, v246
	v_mul_f32_e32 v141, v141, v246
	v_mul_f32_e32 v142, v142, v246
	v_mul_f32_e32 v143, v143, v246
	v_fma_f32 v244, v67, s22, -v198
	v_fma_f32 v245, v71, s22, -v198
	v_fma_f32 v246, v75, s22, -v198
	v_fma_f32 v247, v79, s22, -v198
	v_exp_f32_e32 v244, v244
	v_exp_f32_e32 v245, v245
	v_exp_f32_e32 v246, v246
	v_exp_f32_e32 v247, v247
	v_add_f32_e32 v248, v244, v245
	v_add_f32_e32 v249, v246, v247
	v_cvt_pk_fp8_f32 v250, v244, v245
	v_add_f32_e32 v248, v248, v249
	v_cvt_pk_fp8_f32 v250, v246, v247 op_sel:[0,0,1]
	s_nop 0
	s_branch .Lsb_bk_48
.Lsb_qs_46:
	s_bitcmp1_b32 s54, 2
	s_cbranch_scc0 .Lsb_qs_49
	v_fma_f32 v244, v68, s22, -v200
	v_fma_f32 v245, v72, s22, -v200
	v_fma_f32 v246, v76, s22, -v200
	v_fma_f32 v247, v80, s22, -v200
	v_exp_f32_e32 v244, v244
	v_exp_f32_e32 v245, v245
	v_exp_f32_e32 v246, v246
	v_exp_f32_e32 v247, v247
	v_add_f32_e32 v248, v244, v245
	v_add_f32_e32 v249, v246, v247
	v_cvt_pk_fp8_f32 v250, v244, v245
	v_add_f32_e32 v248, v248, v249
	v_cvt_pk_fp8_f32 v250, v246, v247 op_sel:[0,0,1]
	v_cmp_lt_f32_e32 vcc, 0x43800000, v248
	s_nop 0
	s_cbranch_vccnz .Lsb_sl_50
.Lsb_bk_51:
	v_cmp_eq_u32_e32 vcc, 2, v165
	v_add_f32_e32 v133, v133, v248
	v_mov_b32_dpp v244, v250 quad_perm:[0,0,0,0] row_mask:0xf bank_mask:0xf
	v_mov_b32_dpp v245, v250 quad_perm:[1,1,1,1] row_mask:0xf bank_mask:0xf
	v_mov_b32_dpp v246, v250 quad_perm:[2,2,2,2] row_mask:0xf bank_mask:0xf
	v_mov_b32_dpp v247, v250 quad_perm:[3,3,3,3] row_mask:0xf bank_mask:0xf
	v_cndmask_b32_e32 v154, v154, v244, vcc
	v_cndmask_b32_e32 v155, v155, v245, vcc
	v_cndmask_b32_e32 v156, v156, v246, vcc
	v_cndmask_b32_e32 v157, v157, v247, vcc
	s_branch .Lsb_qs_49
.Lsb_sl_50:
	v_max3_f32 v244, v68, v72, v76
	v_cmp_eq_u32_e32 vcc, 2, v165
	v_max_f32_e32 v244, v244, v80
	s_nop 1
	v_max_f32_dpp v244, v244, v244 quad_perm:[1,0,3,2] row_mask:0xf bank_mask:0xf
	s_nop 1
	v_max_f32_dpp v244, v244, v244 quad_perm:[2,3,0,1] row_mask:0xf bank_mask:0xf
	s_nop 1
	v_max_f32_dpp v244, v244, v244 row_half_mirror row_mask:0xf bank_mask:0xf
	s_nop 1
	v_max_f32_dpp v244, v244, v244 row_mirror row_mask:0xf bank_mask:0xf
	v_mul_f32_e32 v244, 0x3e38aa3b, v244
	v_max_f32_e32 v244, v200, v244
	v_sub_f32_e32 v245, v200, v244
	v_exp_f32_e32 v245, v245
	v_mov_b32_e32 v200, v244
	s_nop 0
	v_mul_f32_e32 v133, v133, v245
	v_cndmask_b32_e64 v246, 1.0, v245, vcc
	ds_bpermute_b32 v246, v187, v246
	s_waitcnt lgkmcnt(0)
	v_mul_f32_e32 v118, v118, v246
	v_mul_f32_e32 v119, v119, v246
	v_mul_f32_e32 v120, v120, v246
	v_mul_f32_e32 v121, v121, v246
	v_mul_f32_e32 v122, v122, v246
	v_mul_f32_e32 v123, v123, v246
	v_mul_f32_e32 v124, v124, v246
	v_mul_f32_e32 v125, v125, v246
	v_mul_f32_e32 v136, v136, v246
	v_mul_f32_e32 v137, v137, v246
	v_mul_f32_e32 v138, v138, v246
	v_mul_f32_e32 v139, v139, v246
	v_mul_f32_e32 v140, v140, v246
	v_mul_f32_e32 v141, v141, v246
	v_mul_f32_e32 v142, v142, v246
	v_mul_f32_e32 v143, v143, v246
	v_fma_f32 v244, v68, s22, -v200
	v_fma_f32 v245, v72, s22, -v200
	v_fma_f32 v246, v76, s22, -v200
	v_fma_f32 v247, v80, s22, -v200
	v_exp_f32_e32 v244, v244
	v_exp_f32_e32 v245, v245
	v_exp_f32_e32 v246, v246
	v_exp_f32_e32 v247, v247
	v_add_f32_e32 v248, v244, v245
	v_add_f32_e32 v249, v246, v247
	v_cvt_pk_fp8_f32 v250, v244, v245
	v_add_f32_e32 v248, v248, v249
	v_cvt_pk_fp8_f32 v250, v246, v247 op_sel:[0,0,1]
	s_nop 0
	s_branch .Lsb_bk_51
.Lsb_qs_49:
	s_bitcmp1_b32 s54, 3
	s_cbranch_scc0 .Lsb_qs_52
	v_fma_f32 v244, v69, s22, -v202
	v_fma_f32 v245, v73, s22, -v202
	v_fma_f32 v246, v77, s22, -v202
	v_fma_f32 v247, v81, s22, -v202
	v_exp_f32_e32 v244, v244
	v_exp_f32_e32 v245, v245
	v_exp_f32_e32 v246, v246
	v_exp_f32_e32 v247, v247
	v_add_f32_e32 v248, v244, v245
	v_add_f32_e32 v249, v246, v247
	v_cvt_pk_fp8_f32 v250, v244, v245
	v_add_f32_e32 v248, v248, v249
	v_cvt_pk_fp8_f32 v250, v246, v247 op_sel:[0,0,1]
	v_cmp_lt_f32_e32 vcc, 0x43800000, v248
	s_nop 0
	s_cbranch_vccnz .Lsb_sl_53
.Lsb_bk_54:
	v_cmp_eq_u32_e32 vcc, 3, v165
	v_add_f32_e32 v209, v209, v248
	v_mov_b32_dpp v244, v250 quad_perm:[0,0,0,0] row_mask:0xf bank_mask:0xf
	v_mov_b32_dpp v245, v250 quad_perm:[1,1,1,1] row_mask:0xf bank_mask:0xf
	v_mov_b32_dpp v246, v250 quad_perm:[2,2,2,2] row_mask:0xf bank_mask:0xf
	v_mov_b32_dpp v247, v250 quad_perm:[3,3,3,3] row_mask:0xf bank_mask:0xf
	v_cndmask_b32_e32 v154, v154, v244, vcc
	v_cndmask_b32_e32 v155, v155, v245, vcc
	v_cndmask_b32_e32 v156, v156, v246, vcc
	v_cndmask_b32_e32 v157, v157, v247, vcc
	s_branch .Lsb_qs_52
.Lsb_sl_53:
	v_max3_f32 v244, v69, v73, v77
	v_cmp_eq_u32_e32 vcc, 3, v165
	v_max_f32_e32 v244, v244, v81
	s_nop 1
	v_max_f32_dpp v244, v244, v244 quad_perm:[1,0,3,2] row_mask:0xf bank_mask:0xf
	s_nop 1
	v_max_f32_dpp v244, v244, v244 quad_perm:[2,3,0,1] row_mask:0xf bank_mask:0xf
	s_nop 1
	v_max_f32_dpp v244, v244, v244 row_half_mirror row_mask:0xf bank_mask:0xf
	s_nop 1
	v_max_f32_dpp v244, v244, v244 row_mirror row_mask:0xf bank_mask:0xf
	v_mul_f32_e32 v244, 0x3e38aa3b, v244
	v_max_f32_e32 v244, v202, v244
	v_sub_f32_e32 v245, v202, v244
	v_exp_f32_e32 v245, v245
	v_mov_b32_e32 v202, v244
	s_nop 0
	v_mul_f32_e32 v209, v209, v245
	v_cndmask_b32_e64 v246, 1.0, v245, vcc
	ds_bpermute_b32 v246, v187, v246
	s_waitcnt lgkmcnt(0)
	v_mul_f32_e32 v118, v118, v246
	v_mul_f32_e32 v119, v119, v246
	v_mul_f32_e32 v120, v120, v246
	v_mul_f32_e32 v121, v121, v246
	v_mul_f32_e32 v122, v122, v246
	v_mul_f32_e32 v123, v123, v246
	v_mul_f32_e32 v124, v124, v246
	v_mul_f32_e32 v125, v125, v246
	v_mul_f32_e32 v136, v136, v246
	v_mul_f32_e32 v137, v137, v246
	v_mul_f32_e32 v138, v138, v246
	v_mul_f32_e32 v139, v139, v246
	v_mul_f32_e32 v140, v140, v246
	v_mul_f32_e32 v141, v141, v246
	v_mul_f32_e32 v142, v142, v246
	v_mul_f32_e32 v143, v143, v246
	v_fma_f32 v244, v69, s22, -v202
	v_fma_f32 v245, v73, s22, -v202
	v_fma_f32 v246, v77, s22, -v202
	v_fma_f32 v247, v81, s22, -v202
	v_exp_f32_e32 v244, v244
	v_exp_f32_e32 v245, v245
	v_exp_f32_e32 v246, v246
	v_exp_f32_e32 v247, v247
	v_add_f32_e32 v248, v244, v245
	v_add_f32_e32 v249, v246, v247
	v_cvt_pk_fp8_f32 v250, v244, v245
	v_add_f32_e32 v248, v248, v249
	v_cvt_pk_fp8_f32 v250, v246, v247 op_sel:[0,0,1]
	s_nop 0
	s_branch .Lsb_bk_54
.Lsb_qs_52:
	ds_bpermute_b32 v154, v187, v154
	ds_bpermute_b32 v155, v187, v155
	ds_bpermute_b32 v156, v187, v156
	ds_bpermute_b32 v157, v187, v157
	s_waitcnt lgkmcnt(0)
	v_mfma_f32_16x16x32_fp8_fp8 v[118:121], v[18:19], v[154:155], v[118:121]
	v_mfma_f32_16x16x32_fp8_fp8 v[122:125], v[22:23], v[154:155], v[122:125]
	v_mfma_f32_16x16x32_fp8_fp8 v[136:139], v[26:27], v[154:155], v[136:139]
	v_mfma_f32_16x16x32_fp8_fp8 v[140:143], v[30:31], v[154:155], v[140:143]
	v_mfma_f32_16x16x32_fp8_fp8 v[118:121], v[20:21], v[156:157], v[118:121]
	v_mfma_f32_16x16x32_fp8_fp8 v[122:125], v[24:25], v[156:157], v[122:125]
	v_mfma_f32_16x16x32_fp8_fp8 v[136:139], v[28:29], v[156:157], v[136:139]
	v_mfma_f32_16x16x32_fp8_fp8 v[140:143], v[32:33], v[156:157], v[140:143]

.Lsb_wd_63:
	s_bfe_u32 s22, s17, 0x40000
	s_cmp_eq_u32 s22, 0
	s_cbranch_scc1 .Lsb_sg_64
	v_mfma_f32_16x16x32_fp8_fp8 v[66:69], v[144:145], v[34:35], 0
	v_mfma_f32_16x16x32_fp8_fp8 v[70:73], v[144:145], v[38:39], 0
	v_mfma_f32_16x16x32_fp8_fp8 v[74:77], v[144:145], v[42:43], 0
	v_mfma_f32_16x16x32_fp8_fp8 v[78:81], v[144:145], v[46:47], 0
	v_mfma_f32_16x16x32_fp8_fp8 v[66:69], v[146:147], v[36:37], v[66:69]
	v_mfma_f32_16x16x32_fp8_fp8 v[70:73], v[146:147], v[40:41], v[70:73]
	v_mfma_f32_16x16x32_fp8_fp8 v[74:77], v[146:147], v[44:45], v[74:77]
	v_mfma_f32_16x16x32_fp8_fp8 v[78:81], v[146:147], v[48:49], v[78:81]
	v_mov_b32_e32 v154, 0
	v_mov_b32_e32 v155, 0
	v_mov_b32_e32 v156, 0
	v_mov_b32_e32 v157, 0
	s_bfe_u32 s54, s17, 0x40000
	s_mov_b32 s22, 0x3e38aa3b
	s_cmp_lg_u32 s14, s48
	s_nop 3
	s_cbranch_scc1 .Lsb_nd_66
	s_add_i32 s23, s21, 0
	v_cmp_lt_i32_e32 vcc, s23, v201
	s_nop 1
	v_cndmask_b32_e32 v66, v66, v199, vcc
	s_add_i32 s23, s21, -16
	v_cmp_lt_i32_e32 vcc, s23, v201
	s_nop 1
	v_cndmask_b32_e32 v70, v70, v199, vcc
	s_add_i32 s23, s21, -32
	v_cmp_lt_i32_e32 vcc, s23, v201
	s_nop 1
	v_cndmask_b32_e32 v74, v74, v199, vcc
	s_add_i32 s23, s21, -48
	v_cmp_lt_i32_e32 vcc, s23, v201
	s_nop 1
	v_cndmask_b32_e32 v78, v78, v199, vcc
	s_add_i32 s23, s21, 1
	v_cmp_lt_i32_e32 vcc, s23, v201
	s_nop 1
	v_cndmask_b32_e32 v67, v67, v199, vcc
	s_add_i32 s23, s21, -15
	v_cmp_lt_i32_e32 vcc, s23, v201
	s_nop 1
	v_cndmask_b32_e32 v71, v71, v199, vcc
	s_add_i32 s23, s21, -31
	v_cmp_lt_i32_e32 vcc, s23, v201
	s_nop 1
	v_cndmask_b32_e32 v75, v75, v199, vcc
	s_add_i32 s23, s21, -47
	v_cmp_lt_i32_e32 vcc, s23, v201
	s_nop 1
	v_cndmask_b32_e32 v79, v79, v199, vcc
	s_add_i32 s23, s21, 2
	v_cmp_lt_i32_e32 vcc, s23, v201
	s_nop 1
	v_cndmask_b32_e32 v68, v68, v199, vcc
	s_add_i32 s23, s21, -14
	v_cmp_lt_i32_e32 vcc, s23, v201
	s_nop 1
	v_cndmask_b32_e32 v72, v72, v199, vcc
	s_add_i32 s23, s21, -30
	v_cmp_lt_i32_e32 vcc, s23, v201
	s_nop 1
	v_cndmask_b32_e32 v76, v76, v199, vcc
	s_add_i32 s23, s21, -46
	v_cmp_lt_i32_e32 vcc, s23, v201
	s_nop 1
	v_cndmask_b32_e32 v80, v80, v199, vcc
	s_add_i32 s23, s21, 3
	v_cmp_lt_i32_e32 vcc, s23, v201
	s_nop 1
	v_cndmask_b32_e32 v69, v69, v199, vcc
	s_add_i32 s23, s21, -13
	v_cmp_lt_i32_e32 vcc, s23, v201
	s_nop 1
	v_cndmask_b32_e32 v73, v73, v199, vcc
	s_add_i32 s23, s21, -29
	v_cmp_lt_i32_e32 vcc, s23, v201
	s_nop 1
	v_cndmask_b32_e32 v77, v77, v199, vcc
	s_add_i32 s23, s21, -45
	v_cmp_lt_i32_e32 vcc, s23, v201
	s_nop 1
	v_cndmask_b32_e32 v81, v81, v199, vcc

.Lsb_qs_76:
	ds_bpermute_b32 v154, v187, v154
	ds_bpermute_b32 v155, v187, v155
	ds_bpermute_b32 v156, v187, v156
	ds_bpermute_b32 v157, v187, v157
	s_waitcnt lgkmcnt(0)
	v_mfma_f32_16x16x32_fp8_fp8 v[102:105], v[50:51], v[154:155], v[102:105]
	v_mfma_f32_16x16x32_fp8_fp8 v[106:109], v[54:55], v[154:155], v[106:109]
	v_mfma_f32_16x16x32_fp8_fp8 v[110:113], v[58:59], v[154:155], v[110:113]
	v_mfma_f32_16x16x32_fp8_fp8 v[114:117], v[62:63], v[154:155], v[114:117]
	v_mfma_f32_16x16x32_fp8_fp8 v[102:105], v[52:53], v[156:157], v[102:105]
	v_mfma_f32_16x16x32_fp8_fp8 v[106:109], v[56:57], v[156:157], v[106:109]
	v_mfma_f32_16x16x32_fp8_fp8 v[110:113], v[60:61], v[156:157], v[110:113]
	v_mfma_f32_16x16x32_fp8_fp8 v[114:117], v[64:65], v[156:157], v[114:117]
.Lsb_ce_65:
.Lsb_sg_64:
	s_bfe_u32 s22, s17, 0x40004
	s_cmp_eq_u32 s22, 0
	s_cbranch_scc1 .Lsb_sg_79
	v_mfma_f32_16x16x32_fp8_fp8 v[66:69], v[150:151], v[34:35], 0
	v_mfma_f32_16x16x32_fp8_fp8 v[70:73], v[150:151], v[38:39], 0
	v_mfma_f32_16x16x32_fp8_fp8 v[74:77], v[150:151], v[42:43], 0
	v_mfma_f32_16x16x32_fp8_fp8 v[78:81], v[150:151], v[46:47], 0
	v_mfma_f32_16x16x32_fp8_fp8 v[66:69], v[152:153], v[36:37], v[66:69]
	v_mfma_f32_16x16x32_fp8_fp8 v[70:73], v[152:153], v[40:41], v[70:73]
	v_mfma_f32_16x16x32_fp8_fp8 v[74:77], v[152:153], v[44:45], v[74:77]
	v_mfma_f32_16x16x32_fp8_fp8 v[78:81], v[152:153], v[48:49], v[78:81]
	v_mov_b32_e32 v154, 0
	v_mov_b32_e32 v155, 0
	v_mov_b32_e32 v156, 0
	v_mov_b32_e32 v157, 0
	s_bfe_u32 s54, s17, 0x40004
	s_mov_b32 s22, 0x3e38aa3b
	s_cmp_lg_u32 s14, s48
	s_nop 3
	s_cbranch_scc1 .Lsb_nd_81
	s_add_i32 s23, s21, 4
	v_cmp_lt_i32_e32 vcc, s23, v201
	s_nop 1
	v_cndmask_b32_e32 v66, v66, v199, vcc
	s_add_i32 s23, s21, -12
	v_cmp_lt_i32_e32 vcc, s23, v201
	s_nop 1
	v_cndmask_b32_e32 v70, v70, v199, vcc
	s_add_i32 s23, s21, -28
	v_cmp_lt_i32_e32 vcc, s23, v201
	s_nop 1
	v_cndmask_b32_e32 v74, v74, v199, vcc
	s_add_i32 s23, s21, -44
	v_cmp_lt_i32_e32 vcc, s23, v201
	s_nop 1
	v_cndmask_b32_e32 v78, v78, v199, vcc
	s_add_i32 s23, s21, 5
	v_cmp_lt_i32_e32 vcc, s23, v201
	s_nop 1
	v_cndmask_b32_e32 v67, v67, v199, vcc
	s_add_i32 s23, s21, -11
	v_cmp_lt_i32_e32 vcc, s23, v201
	s_nop 1
	v_cndmask_b32_e32 v71, v71, v199, vcc
	s_add_i32 s23, s21, -27
	v_cmp_lt_i32_e32 vcc, s23, v201
	s_nop 1
	v_cndmask_b32_e32 v75, v75, v199, vcc
	s_add_i32 s23, s21, -43
	v_cmp_lt_i32_e32 vcc, s23, v201
	s_nop 1
	v_cndmask_b32_e32 v79, v79, v199, vcc
	s_add_i32 s23, s21, 6
	v_cmp_lt_i32_e32 vcc, s23, v201
	s_nop 1
	v_cndmask_b32_e32 v68, v68, v199, vcc
	s_add_i32 s23, s21, -10
	v_cmp_lt_i32_e32 vcc, s23, v201
	s_nop 1
	v_cndmask_b32_e32 v72, v72, v199, vcc
	s_add_i32 s23, s21, -26
	v_cmp_lt_i32_e32 vcc, s23, v201
	s_nop 1
	v_cndmask_b32_e32 v76, v76, v199, vcc
	s_add_i32 s23, s21, -42
	v_cmp_lt_i32_e32 vcc, s23, v201
	s_nop 1
	v_cndmask_b32_e32 v80, v80, v199, vcc
	s_add_i32 s23, s21, 7
	v_cmp_lt_i32_e32 vcc, s23, v201
	s_nop 1
	v_cndmask_b32_e32 v69, v69, v199, vcc
	s_add_i32 s23, s21, -9
	v_cmp_lt_i32_e32 vcc, s23, v201
	s_nop 1
	v_cndmask_b32_e32 v73, v73, v199, vcc
	s_add_i32 s23, s21, -25
	v_cmp_lt_i32_e32 vcc, s23, v201
	s_nop 1
	v_cndmask_b32_e32 v77, v77, v199, vcc
	s_add_i32 s23, s21, -41
	v_cmp_lt_i32_e32 vcc, s23, v201
	s_nop 1
	v_cndmask_b32_e32 v81, v81, v199, vcc

.Lsb_qs_91:
	ds_bpermute_b32 v154, v187, v154
	ds_bpermute_b32 v155, v187, v155
	ds_bpermute_b32 v156, v187, v156
	ds_bpermute_b32 v157, v187, v157
	s_waitcnt lgkmcnt(0)
	v_mfma_f32_16x16x32_fp8_fp8 v[118:121], v[50:51], v[154:155], v[118:121]
	v_mfma_f32_16x16x32_fp8_fp8 v[122:125], v[54:55], v[154:155], v[122:125]
	v_mfma_f32_16x16x32_fp8_fp8 v[136:139], v[58:59], v[154:155], v[136:139]
	v_mfma_f32_16x16x32_fp8_fp8 v[140:143], v[62:63], v[154:155], v[140:143]
	v_mfma_f32_16x16x32_fp8_fp8 v[118:121], v[52:53], v[156:157], v[118:121]
	v_mfma_f32_16x16x32_fp8_fp8 v[122:125], v[56:57], v[156:157], v[122:125]
	v_mfma_f32_16x16x32_fp8_fp8 v[136:139], v[60:61], v[156:157], v[136:139]
	v_mfma_f32_16x16x32_fp8_fp8 v[140:143], v[64:65], v[156:157], v[140:143]

.Lsb_wd_102:
	s_bfe_u32 s22, s17, 0x40000
	s_cmp_eq_u32 s22, 0
	s_cbranch_scc1 .Lsb_sg_103
	v_mfma_f32_16x16x32_fp8_fp8 v[66:69], v[144:145], v[212:213], 0
	v_mfma_f32_16x16x32_fp8_fp8 v[70:73], v[144:145], v[216:217], 0
	v_mfma_f32_16x16x32_fp8_fp8 v[74:77], v[144:145], v[220:221], 0
	v_mfma_f32_16x16x32_fp8_fp8 v[78:81], v[144:145], v[224:225], 0
	v_mfma_f32_16x16x32_fp8_fp8 v[66:69], v[146:147], v[214:215], v[66:69]
	v_mfma_f32_16x16x32_fp8_fp8 v[70:73], v[146:147], v[218:219], v[70:73]
	v_mfma_f32_16x16x32_fp8_fp8 v[74:77], v[146:147], v[222:223], v[74:77]
	v_mfma_f32_16x16x32_fp8_fp8 v[78:81], v[146:147], v[226:227], v[78:81]
	v_mov_b32_e32 v154, 0
	v_mov_b32_e32 v155, 0
	v_mov_b32_e32 v156, 0
	v_mov_b32_e32 v157, 0
	s_bfe_u32 s54, s17, 0x40000
	s_mov_b32 s22, 0x3e38aa3b
	s_cmp_lg_u32 s14, s48
	s_nop 3
	s_cbranch_scc1 .Lsb_nd_105
	s_add_i32 s23, s21, 0
	v_cmp_lt_i32_e32 vcc, s23, v201
	s_nop 1
	v_cndmask_b32_e32 v66, v66, v199, vcc
	s_add_i32 s23, s21, -16
	v_cmp_lt_i32_e32 vcc, s23, v201
	s_nop 1
	v_cndmask_b32_e32 v70, v70, v199, vcc
	s_add_i32 s23, s21, -32
	v_cmp_lt_i32_e32 vcc, s23, v201
	s_nop 1
	v_cndmask_b32_e32 v74, v74, v199, vcc
	s_add_i32 s23, s21, -48
	v_cmp_lt_i32_e32 vcc, s23, v201
	s_nop 1
	v_cndmask_b32_e32 v78, v78, v199, vcc
	s_add_i32 s23, s21, 1
	v_cmp_lt_i32_e32 vcc, s23, v201
	s_nop 1
	v_cndmask_b32_e32 v67, v67, v199, vcc
	s_add_i32 s23, s21, -15
	v_cmp_lt_i32_e32 vcc, s23, v201
	s_nop 1
	v_cndmask_b32_e32 v71, v71, v199, vcc
	s_add_i32 s23, s21, -31
	v_cmp_lt_i32_e32 vcc, s23, v201
	s_nop 1
	v_cndmask_b32_e32 v75, v75, v199, vcc
	s_add_i32 s23, s21, -47
	v_cmp_lt_i32_e32 vcc, s23, v201
	s_nop 1
	v_cndmask_b32_e32 v79, v79, v199, vcc
	s_add_i32 s23, s21, 2
	v_cmp_lt_i32_e32 vcc, s23, v201
	s_nop 1
	v_cndmask_b32_e32 v68, v68, v199, vcc
	s_add_i32 s23, s21, -14
	v_cmp_lt_i32_e32 vcc, s23, v201
	s_nop 1
	v_cndmask_b32_e32 v72, v72, v199, vcc
	s_add_i32 s23, s21, -30
	v_cmp_lt_i32_e32 vcc, s23, v201
	s_nop 1
	v_cndmask_b32_e32 v76, v76, v199, vcc
	s_add_i32 s23, s21, -46
	v_cmp_lt_i32_e32 vcc, s23, v201
	s_nop 1
	v_cndmask_b32_e32 v80, v80, v199, vcc
	s_add_i32 s23, s21, 3
	v_cmp_lt_i32_e32 vcc, s23, v201
	s_nop 1
	v_cndmask_b32_e32 v69, v69, v199, vcc
	s_add_i32 s23, s21, -13
	v_cmp_lt_i32_e32 vcc, s23, v201
	s_nop 1
	v_cndmask_b32_e32 v73, v73, v199, vcc
	s_add_i32 s23, s21, -29
	v_cmp_lt_i32_e32 vcc, s23, v201
	s_nop 1
	v_cndmask_b32_e32 v77, v77, v199, vcc
	s_add_i32 s23, s21, -45
	v_cmp_lt_i32_e32 vcc, s23, v201
	s_nop 1
	v_cndmask_b32_e32 v81, v81, v199, vcc

.Lsb_qs_115:
	ds_bpermute_b32 v154, v187, v154
	ds_bpermute_b32 v155, v187, v155
	ds_bpermute_b32 v156, v187, v156
	ds_bpermute_b32 v157, v187, v157
	s_waitcnt lgkmcnt(0)
	v_mfma_f32_16x16x32_fp8_fp8 v[102:105], v[228:229], v[154:155], v[102:105]
	v_mfma_f32_16x16x32_fp8_fp8 v[106:109], v[232:233], v[154:155], v[106:109]
	v_mfma_f32_16x16x32_fp8_fp8 v[110:113], v[236:237], v[154:155], v[110:113]
	v_mfma_f32_16x16x32_fp8_fp8 v[114:117], v[240:241], v[154:155], v[114:117]
	v_mfma_f32_16x16x32_fp8_fp8 v[102:105], v[230:231], v[156:157], v[102:105]
	v_mfma_f32_16x16x32_fp8_fp8 v[106:109], v[234:235], v[156:157], v[106:109]
	v_mfma_f32_16x16x32_fp8_fp8 v[110:113], v[238:239], v[156:157], v[110:113]
	v_mfma_f32_16x16x32_fp8_fp8 v[114:117], v[242:243], v[156:157], v[114:117]
.Lsb_ce_104:
.Lsb_sg_103:
	s_bfe_u32 s22, s17, 0x40004
	s_cmp_eq_u32 s22, 0
	s_cbranch_scc1 .Lsb_sg_118
	v_mfma_f32_16x16x32_fp8_fp8 v[66:69], v[150:151], v[212:213], 0
	v_mfma_f32_16x16x32_fp8_fp8 v[70:73], v[150:151], v[216:217], 0
	v_mfma_f32_16x16x32_fp8_fp8 v[74:77], v[150:151], v[220:221], 0
	v_mfma_f32_16x16x32_fp8_fp8 v[78:81], v[150:151], v[224:225], 0
	v_mfma_f32_16x16x32_fp8_fp8 v[66:69], v[152:153], v[214:215], v[66:69]
	v_mfma_f32_16x16x32_fp8_fp8 v[70:73], v[152:153], v[218:219], v[70:73]
	v_mfma_f32_16x16x32_fp8_fp8 v[74:77], v[152:153], v[222:223], v[74:77]
	v_mfma_f32_16x16x32_fp8_fp8 v[78:81], v[152:153], v[226:227], v[78:81]
	v_mov_b32_e32 v154, 0
	v_mov_b32_e32 v155, 0
	v_mov_b32_e32 v156, 0
	v_mov_b32_e32 v157, 0
	s_bfe_u32 s54, s17, 0x40004
	s_mov_b32 s22, 0x3e38aa3b
	s_cmp_lg_u32 s14, s48
	s_nop 3
	s_cbranch_scc1 .Lsb_nd_120
	s_add_i32 s23, s21, 4
	v_cmp_lt_i32_e32 vcc, s23, v201
	s_nop 1
	v_cndmask_b32_e32 v66, v66, v199, vcc
	s_add_i32 s23, s21, -12
	v_cmp_lt_i32_e32 vcc, s23, v201
	s_nop 1
	v_cndmask_b32_e32 v70, v70, v199, vcc
	s_add_i32 s23, s21, -28
	v_cmp_lt_i32_e32 vcc, s23, v201
	s_nop 1
	v_cndmask_b32_e32 v74, v74, v199, vcc
	s_add_i32 s23, s21, -44
	v_cmp_lt_i32_e32 vcc, s23, v201
	s_nop 1
	v_cndmask_b32_e32 v78, v78, v199, vcc
	s_add_i32 s23, s21, 5
	v_cmp_lt_i32_e32 vcc, s23, v201
	s_nop 1
	v_cndmask_b32_e32 v67, v67, v199, vcc
	s_add_i32 s23, s21, -11
	v_cmp_lt_i32_e32 vcc, s23, v201
	s_nop 1
	v_cndmask_b32_e32 v71, v71, v199, vcc
	s_add_i32 s23, s21, -27
	v_cmp_lt_i32_e32 vcc, s23, v201
	s_nop 1
	v_cndmask_b32_e32 v75, v75, v199, vcc
	s_add_i32 s23, s21, -43
	v_cmp_lt_i32_e32 vcc, s23, v201
	s_nop 1
	v_cndmask_b32_e32 v79, v79, v199, vcc
	s_add_i32 s23, s21, 6
	v_cmp_lt_i32_e32 vcc, s23, v201
	s_nop 1
	v_cndmask_b32_e32 v68, v68, v199, vcc
	s_add_i32 s23, s21, -10
	v_cmp_lt_i32_e32 vcc, s23, v201
	s_nop 1
	v_cndmask_b32_e32 v72, v72, v199, vcc
	s_add_i32 s23, s21, -26
	v_cmp_lt_i32_e32 vcc, s23, v201
	s_nop 1
	v_cndmask_b32_e32 v76, v76, v199, vcc
	s_add_i32 s23, s21, -42
	v_cmp_lt_i32_e32 vcc, s23, v201
	s_nop 1
	v_cndmask_b32_e32 v80, v80, v199, vcc
	s_add_i32 s23, s21, 7
	v_cmp_lt_i32_e32 vcc, s23, v201
	s_nop 1
	v_cndmask_b32_e32 v69, v69, v199, vcc
	s_add_i32 s23, s21, -9
	v_cmp_lt_i32_e32 vcc, s23, v201
	s_nop 1
	v_cndmask_b32_e32 v73, v73, v199, vcc
	s_add_i32 s23, s21, -25
	v_cmp_lt_i32_e32 vcc, s23, v201
	s_nop 1
	v_cndmask_b32_e32 v77, v77, v199, vcc
	s_add_i32 s23, s21, -41
	v_cmp_lt_i32_e32 vcc, s23, v201
	s_nop 1
	v_cndmask_b32_e32 v81, v81, v199, vcc

.Lsb_qs_130:
	ds_bpermute_b32 v154, v187, v154
	ds_bpermute_b32 v155, v187, v155
	ds_bpermute_b32 v156, v187, v156
	ds_bpermute_b32 v157, v187, v157
	s_waitcnt lgkmcnt(0)
	v_mfma_f32_16x16x32_fp8_fp8 v[118:121], v[228:229], v[154:155], v[118:121]
	v_mfma_f32_16x16x32_fp8_fp8 v[122:125], v[232:233], v[154:155], v[122:125]
	v_mfma_f32_16x16x32_fp8_fp8 v[136:139], v[236:237], v[154:155], v[136:139]
	v_mfma_f32_16x16x32_fp8_fp8 v[140:143], v[240:241], v[154:155], v[140:143]
	v_mfma_f32_16x16x32_fp8_fp8 v[118:121], v[230:231], v[156:157], v[118:121]
	v_mfma_f32_16x16x32_fp8_fp8 v[122:125], v[234:235], v[156:157], v[122:125]
	v_mfma_f32_16x16x32_fp8_fp8 v[136:139], v[238:239], v[156:157], v[136:139]
	v_mfma_f32_16x16x32_fp8_fp8 v[140:143], v[242:243], v[156:157], v[140:143]

.Lsb_exit:
	s_waitcnt vmcnt(0)
	v_add_f32_dpp v204, v204, v204 quad_perm:[1,0,3,2] row_mask:0xf bank_mask:0xf
	v_add_f32_dpp v205, v205, v205 quad_perm:[1,0,3,2] row_mask:0xf bank_mask:0xf
	v_add_f32_dpp v252, v252, v252 quad_perm:[1,0,3,2] row_mask:0xf bank_mask:0xf
	v_add_f32_dpp v253, v253, v253 quad_perm:[1,0,3,2] row_mask:0xf bank_mask:0xf
	v_add_f32_dpp v204, v204, v204 quad_perm:[2,3,0,1] row_mask:0xf bank_mask:0xf
	v_add_f32_dpp v205, v205, v205 quad_perm:[2,3,0,1] row_mask:0xf bank_mask:0xf
	v_add_f32_dpp v252, v252, v252 quad_perm:[2,3,0,1] row_mask:0xf bank_mask:0xf
	v_add_f32_dpp v253, v253, v253 quad_perm:[2,3,0,1] row_mask:0xf bank_mask:0xf
	v_add_f32_dpp v204, v204, v204 row_half_mirror row_mask:0xf bank_mask:0xf
	v_add_f32_dpp v205, v205, v205 row_half_mirror row_mask:0xf bank_mask:0xf
	v_add_f32_dpp v252, v252, v252 row_half_mirror row_mask:0xf bank_mask:0xf
	v_add_f32_dpp v253, v253, v253 row_half_mirror row_mask:0xf bank_mask:0xf
	v_add_f32_dpp v204, v204, v204 row_mirror row_mask:0xf bank_mask:0xf
	v_add_f32_dpp v205, v205, v205 row_mirror row_mask:0xf bank_mask:0xf
	v_add_f32_dpp v252, v252, v252 row_mirror row_mask:0xf bank_mask:0xf
	v_add_f32_dpp v253, v253, v253 row_mirror row_mask:0xf bank_mask:0xf
	v_cmp_eq_u32_e32 vcc, 1, v165
	v_cmp_eq_u32_e64 s[22:23], 2, v165
	v_cmp_eq_u32_e64 s[12:13], 3, v165
	s_nop 0
	v_cndmask_b32_e32 v203, v204, v205, vcc
	v_cndmask_b32_e64 v203, v203, v252, s[22:23]
	v_cndmask_b32_e64 v203, v203, v253, s[12:13]
	ds_bpermute_b32 v203, v187, v203
	s_waitcnt lgkmcnt(0)
	v_div_scale_f32 v244, s[22:23], v203, v203, v208
	v_rcp_f32_e32 v245, v244
	s_nop 0
	v_fma_f32 v246, -v244, v245, 1.0
	v_fmac_f32_e32 v245, v246, v245
	v_div_scale_f32 v246, vcc, v208, v203, v208
	v_mul_f32_e32 v247, v246, v245
	v_fma_f32 v248, -v244, v247, v246
	v_fmac_f32_e32 v247, v248, v245
	v_fma_f32 v244, -v244, v247, v246
	v_div_fmas_f32 v244, v244, v245, v247
	v_div_fixup_f32 v203, v244, v203, v208
	ds_read2_b64 v[244:247], v207 offset0:0 offset1:4
	s_waitcnt lgkmcnt(0)
	v_lshlrev_b32_e32 v248, 16, v244
	v_and_b32_e32 v249, 0xffff0000, v244
	v_lshlrev_b32_e32 v250, 16, v245
	v_and_b32_e32 v251, 0xffff0000, v245
	v_fma_f32 v248, v102, v203, v248
	v_fma_f32 v249, v103, v203, v249
	v_fma_f32 v250, v104, v203, v250
	v_fma_f32 v251, v105, v203, v251
	v_cvt_pk_bf16_f32 v244, v248, v249
	v_cvt_pk_bf16_f32 v245, v250, v251
	v_lshlrev_b32_e32 v248, 16, v246
	v_and_b32_e32 v249, 0xffff0000, v246
	v_lshlrev_b32_e32 v250, 16, v247
	v_and_b32_e32 v251, 0xffff0000, v247
	v_fma_f32 v248, v106, v203, v248
	v_fma_f32 v249, v107, v203, v249
	v_fma_f32 v250, v108, v203, v250
	v_fma_f32 v251, v109, v203, v251
	v_cvt_pk_bf16_f32 v246, v248, v249
	v_cvt_pk_bf16_f32 v247, v250, v251
	ds_write2_b64 v207, v[244:245], v[246:247] offset0:0 offset1:4
	ds_read2_b64 v[244:247], v207 offset0:8 offset1:12
	s_waitcnt lgkmcnt(0)
	v_lshlrev_b32_e32 v248, 16, v244
	v_and_b32_e32 v249, 0xffff0000, v244
	v_lshlrev_b32_e32 v250, 16, v245
	v_and_b32_e32 v251, 0xffff0000, v245
	v_fma_f32 v248, v110, v203, v248
	v_fma_f32 v249, v111, v203, v249
	v_fma_f32 v250, v112, v203, v250
	v_fma_f32 v251, v113, v203, v251
	v_cvt_pk_bf16_f32 v244, v248, v249
	v_cvt_pk_bf16_f32 v245, v250, v251
	v_lshlrev_b32_e32 v248, 16, v246
	v_and_b32_e32 v249, 0xffff0000, v246
	v_lshlrev_b32_e32 v250, 16, v247
	v_and_b32_e32 v251, 0xffff0000, v247
	v_fma_f32 v248, v114, v203, v248
	v_fma_f32 v249, v115, v203, v249
	v_fma_f32 v250, v116, v203, v250
	v_fma_f32 v251, v117, v203, v251
	v_cvt_pk_bf16_f32 v246, v248, v249
	v_cvt_pk_bf16_f32 v247, v250, v251
	ds_write2_b64 v207, v[244:245], v[246:247] offset0:8 offset1:12
	v_add_u32_e32 v207, 0x800, v207
	v_add_f32_dpp v206, v206, v206 quad_perm:[1,0,3,2] row_mask:0xf bank_mask:0xf
	v_add_f32_dpp v1, v1, v1 quad_perm:[1,0,3,2] row_mask:0xf bank_mask:0xf
	v_add_f32_dpp v133, v133, v133 quad_perm:[1,0,3,2] row_mask:0xf bank_mask:0xf
	v_add_f32_dpp v209, v209, v209 quad_perm:[1,0,3,2] row_mask:0xf bank_mask:0xf
	v_add_f32_dpp v206, v206, v206 quad_perm:[2,3,0,1] row_mask:0xf bank_mask:0xf
	v_add_f32_dpp v1, v1, v1 quad_perm:[2,3,0,1] row_mask:0xf bank_mask:0xf
	v_add_f32_dpp v133, v133, v133 quad_perm:[2,3,0,1] row_mask:0xf bank_mask:0xf
	v_add_f32_dpp v209, v209, v209 quad_perm:[2,3,0,1] row_mask:0xf bank_mask:0xf
	v_add_f32_dpp v206, v206, v206 row_half_mirror row_mask:0xf bank_mask:0xf
	v_add_f32_dpp v1, v1, v1 row_half_mirror row_mask:0xf bank_mask:0xf
	v_add_f32_dpp v133, v133, v133 row_half_mirror row_mask:0xf bank_mask:0xf
	v_add_f32_dpp v209, v209, v209 row_half_mirror row_mask:0xf bank_mask:0xf
	v_add_f32_dpp v206, v206, v206 row_mirror row_mask:0xf bank_mask:0xf
	v_add_f32_dpp v1, v1, v1 row_mirror row_mask:0xf bank_mask:0xf
	v_add_f32_dpp v133, v133, v133 row_mirror row_mask:0xf bank_mask:0xf
	v_add_f32_dpp v209, v209, v209 row_mirror row_mask:0xf bank_mask:0xf
	v_cmp_eq_u32_e32 vcc, 1, v165
	v_cmp_eq_u32_e64 s[22:23], 2, v165
	v_cmp_eq_u32_e64 s[12:13], 3, v165
	s_nop 0
	v_cndmask_b32_e32 v203, v206, v1, vcc
	v_cndmask_b32_e64 v203, v203, v133, s[22:23]
	v_cndmask_b32_e64 v203, v203, v209, s[12:13]
	ds_bpermute_b32 v203, v187, v203
	s_waitcnt lgkmcnt(0)
	v_div_scale_f32 v244, s[22:23], v203, v203, v148
	v_rcp_f32_e32 v245, v244
	s_nop 0
	v_fma_f32 v246, -v244, v245, 1.0
	v_fmac_f32_e32 v245, v246, v245
	v_div_scale_f32 v246, vcc, v148, v203, v148
	v_mul_f32_e32 v247, v246, v245
	v_fma_f32 v248, -v244, v247, v246
	v_fmac_f32_e32 v247, v248, v245
	v_fma_f32 v244, -v244, v247, v246
	v_div_fmas_f32 v244, v244, v245, v247
	v_div_fixup_f32 v203, v244, v203, v148
	ds_read2_b64 v[244:247], v207 offset0:0 offset1:4
	s_waitcnt lgkmcnt(0)
	v_lshlrev_b32_e32 v248, 16, v244
	v_and_b32_e32 v249, 0xffff0000, v244
	v_lshlrev_b32_e32 v250, 16, v245
	v_and_b32_e32 v251, 0xffff0000, v245
	v_fma_f32 v248, v118, v203, v248
	v_fma_f32 v249, v119, v203, v249
	v_fma_f32 v250, v120, v203, v250
	v_fma_f32 v251, v121, v203, v251
	v_cvt_pk_bf16_f32 v244, v248, v249
	v_cvt_pk_bf16_f32 v245, v250, v251
	v_lshlrev_b32_e32 v248, 16, v246
	v_and_b32_e32 v249, 0xffff0000, v246
	v_lshlrev_b32_e32 v250, 16, v247
	v_and_b32_e32 v251, 0xffff0000, v247
	v_fma_f32 v248, v122, v203, v248
	v_fma_f32 v249, v123, v203, v249
	v_fma_f32 v250, v124, v203, v250
	v_fma_f32 v251, v125, v203, v251
	v_cvt_pk_bf16_f32 v246, v248, v249
	v_cvt_pk_bf16_f32 v247, v250, v251
	ds_write2_b64 v207, v[244:245], v[246:247] offset0:0 offset1:4
	ds_read2_b64 v[244:247], v207 offset0:8 offset1:12
	s_waitcnt lgkmcnt(0)
	v_lshlrev_b32_e32 v248, 16, v244
	v_and_b32_e32 v249, 0xffff0000, v244
	v_lshlrev_b32_e32 v250, 16, v245
	v_and_b32_e32 v251, 0xffff0000, v245
	v_fma_f32 v248, v136, v203, v248
	v_fma_f32 v249, v137, v203, v249
	v_fma_f32 v250, v138, v203, v250
	v_fma_f32 v251, v139, v203, v251
	v_cvt_pk_bf16_f32 v244, v248, v249
	v_cvt_pk_bf16_f32 v245, v250, v251
	v_lshlrev_b32_e32 v248, 16, v246
	v_and_b32_e32 v249, 0xffff0000, v246
	v_lshlrev_b32_e32 v250, 16, v247
	v_and_b32_e32 v251, 0xffff0000, v247
	v_fma_f32 v248, v140, v203, v248
	v_fma_f32 v249, v141, v203, v249
	v_fma_f32 v250, v142, v203, v250
	v_fma_f32 v251, v143, v203, v251
	v_cvt_pk_bf16_f32 v246, v248, v249
	v_cvt_pk_bf16_f32 v247, v250, v251
	ds_write2_b64 v207, v[244:245], v[246:247] offset0:8 offset1:12
